# k-inner MFMA pairs, pairs ordered n-major (weights operand slow axis)
# speedup vs baseline: 1.0042x; 1.0042x over previous
; #define PG8_STAGE(bufoff, gbase, voff) do { _Pragma("unroll") for (int _i = 0; _i < 2; ++_i) \
;         __builtin_amdgcn_global_load_lds((const unsigned*)((const char*)(gbase) + (voff)[_i]), (LAS unsigned*)(lds + (bufoff) + ldsw + _i * 8192), 16, 0, 0); } while (0)
; #define PG8_LDA(dst, b, h) do { _Pragma("unroll") for (int m = 0; m < 4; ++m) _Pragma("unroll") for (int k = 0; k < 2; ++k) dst[m][k] = *(const LAS bf16x8*)(lds + PG8_SA(b, h) + aoff + m * 2048 + k * 1024); } while (0)
; #define PG8_LDB(dst, b, h) do { _Pragma("unroll") for (int n = 0; n < 2; ++n) _Pragma("unroll") for (int k = 0; k < 2; ++k) dst[n][k] = *(const LAS bf16x8*)(lds + PG8_SB(b, h) + boff + n * 2048 + k * 1024); } while (0)
; #define PG8_MMA(ai, bj, At, Bt) do { __builtin_amdgcn_s_setprio(1); _Pragma("unroll") for (int m = 0; m < 4; ++m) _Pragma("unroll") for (int n = 0; n < 2; ++n) _Pragma("unroll") for (int k = 0; k < 2; ++k) \
;         acc[ai][bj][m][n] = __builtin_amdgcn_mfma_f32_16x16x32_bf16(Bt[n][k], At[m][k], acc[ai][bj][m][n], 0, 0, 0); __builtin_amdgcn_s_setprio(0); } while (0)
; #define PG8_WAIT_V(n) asm volatile("s_waitcnt vmcnt(" #n ")" ::: "memory")
; #define PG8_WAIT_L(n) asm volatile("s_waitcnt lgkmcnt(" #n ")" ::: "memory")
; #define PG8_BAR __builtin_amdgcn_s_barrier()
; template <class Epi, class Sched, bool ALIGN_EPI = false, bool SP2 = false>
; __device__ __forceinline__ void gemm_phase(LAS unsigned char* lds, const Gemm g, const Sched& S, const Epi& E) {
;     ...
;             const bool last = (t == nt - 2);
;             const char* a1 = cA + (size_t)(t + 1) * kstep;
;             const char* a2 = last ? nA : cA + (size_t)(t + 2) * kstep; const char* b2 = last ? nB : cB + (size_t)(t + 2) * kstep;
;             const char* a3 = a2 + kstep; const char* b3 = b2 + kstep;
;             if (last && has_next) S.a_ready(nxt);
;             if constexpr (SP2) {
;             PG8_LDB(B0, 0, 0); PG8_LDB(B1, 0, 1); PG8_SCHED; PG8_LDA(At, 0, 0); PG8_STAGE(PG8_SA(1, 1), a1 + hstep, voffA);
;             PG8_WAIT_V(8); PG8_WAIT_L(0); PG8_BAR; PG8_MMA(0, 0, At, B0); PG8_MMA(0, 1, At, B1); PG8_BAR; PG8_SCHED;
;             PG8_LDA(At, 0, 1); PG8_STAGE(PG8_SB(0, 0), b2, voffB); PG8_STAGE(PG8_SB(0, 1), b2 + hstep, voffB); PG8_STAGE(PG8_SA(0, 0), a2, voffA);
;             PG8_WAIT_V(8); PG8_WAIT_L(0); PG8_BAR; PG8_MMA(1, 0, At, B0); PG8_MMA(1, 1, At, B1); PG8_BAR; PG8_SCHED;
.LBB0_173:
	s_add_u32 s26, s24, 0xfff80080
	s_addc_u32 s27, s25, -1
	s_add_i32 s45, 0, 0x10000
	s_cmp_eq_u32 s44, 28
	s_cselect_b32 s29, s7, s27
	s_cselect_b32 s28, s8, s26
	v_add_u32_e32 v140, s45, v145
	s_cselect_b32 s27, s17, s43
	s_cselect_b32 s26, s19, s35
	s_add_i32 s47, 0, 0x14000
	ds_read_b128 v[150:153], v140
	ds_read_b128 v[154:157], v140 offset:1024
	ds_read_b128 v[158:161], v140 offset:2048
	ds_read_b128 v[162:165], v140 offset:3072
	v_add_u32_e32 v140, s47, v145
	ds_read_b128 v[166:169], v140
	ds_read_b128 v[170:173], v140 offset:1024
	ds_read_b128 v[174:177], v140 offset:2048
	ds_read_b128 v[178:181], v140 offset:3072
	v_lshl_add_u64 v[140:141], s[24:25], 0, v[136:137]
	s_add_i32 m0, s30, 0xc000
	ds_read_b128 v[182:185], v149
	ds_read_b128 v[194:197], v149 offset:1024
	ds_read_b128 v[198:201], v149 offset:2048
	ds_read_b128 v[202:205], v149 offset:3072
	ds_read_b128 v[206:209], v149 offset:4096
	ds_read_b128 v[210:213], v149 offset:5120
	ds_read_b128 v[214:217], v149 offset:6144
	ds_read_b128 v[218:221], v149 offset:7168
	global_load_lds_dwordx4 v[140:141], off
	v_lshl_add_u64 v[140:141], s[24:25], 0, v[138:139]
	s_add_i32 m0, s30, 0xe000
	s_nop 0
	global_load_lds_dwordx4 v[140:141], off
	s_waitcnt vmcnt(8)
	s_waitcnt lgkmcnt(0)
	s_barrier
	s_setprio 1
	s_waitcnt lgkmcnt(0)
	v_mfma_f32_16x16x32_bf16 v[126:129], v[150:153], v[182:185], v[126:129]
	v_mfma_f32_16x16x32_bf16 v[126:129], v[154:157], v[194:197], v[126:129]
	v_mfma_f32_16x16x32_bf16 v[110:113], v[150:153], v[198:201], v[110:113]
	v_mfma_f32_16x16x32_bf16 v[110:113], v[154:157], v[202:205], v[110:113]
	v_mfma_f32_16x16x32_bf16 v[94:97], v[150:153], v[206:209], v[94:97]
	v_mfma_f32_16x16x32_bf16 v[94:97], v[154:157], v[210:213], v[94:97]
	v_mfma_f32_16x16x32_bf16 v[78:81], v[150:153], v[214:217], v[78:81]
	v_mfma_f32_16x16x32_bf16 v[78:81], v[154:157], v[218:221], v[78:81]
	v_mfma_f32_16x16x32_bf16 v[74:77], v[158:161], v[214:217], v[74:77]
	v_mfma_f32_16x16x32_bf16 v[74:77], v[162:165], v[218:221], v[74:77]
	v_mfma_f32_16x16x32_bf16 v[90:93], v[158:161], v[206:209], v[90:93]
	v_mfma_f32_16x16x32_bf16 v[90:93], v[162:165], v[210:213], v[90:93]
	v_mfma_f32_16x16x32_bf16 v[106:109], v[158:161], v[198:201], v[106:109]
	v_mfma_f32_16x16x32_bf16 v[106:109], v[162:165], v[202:205], v[106:109]
	v_mfma_f32_16x16x32_bf16 v[122:125], v[158:161], v[182:185], v[122:125]
	v_mfma_f32_16x16x32_bf16 v[122:125], v[162:165], v[194:197], v[122:125]
	s_setprio 0
	s_setprio 1
	v_mfma_f32_16x16x32_bf16 v[118:121], v[166:169], v[182:185], v[118:121]
	v_mfma_f32_16x16x32_bf16 v[118:121], v[170:173], v[194:197], v[118:121]
	v_mfma_f32_16x16x32_bf16 v[102:105], v[166:169], v[198:201], v[102:105]
	v_mfma_f32_16x16x32_bf16 v[102:105], v[170:173], v[202:205], v[102:105]
	v_mfma_f32_16x16x32_bf16 v[86:89], v[166:169], v[206:209], v[86:89]
	v_mfma_f32_16x16x32_bf16 v[86:89], v[170:173], v[210:213], v[86:89]
	v_mfma_f32_16x16x32_bf16 v[70:73], v[166:169], v[214:217], v[70:73]
	v_mfma_f32_16x16x32_bf16 v[70:73], v[170:173], v[218:221], v[70:73]
	v_mfma_f32_16x16x32_bf16 v[66:69], v[174:177], v[214:217], v[66:69]
	v_mfma_f32_16x16x32_bf16 v[66:69], v[178:181], v[218:221], v[66:69]
	v_mfma_f32_16x16x32_bf16 v[82:85], v[174:177], v[206:209], v[82:85]
	v_mfma_f32_16x16x32_bf16 v[82:85], v[178:181], v[210:213], v[82:85]
	v_mfma_f32_16x16x32_bf16 v[98:101], v[174:177], v[198:201], v[98:101]
	v_mfma_f32_16x16x32_bf16 v[98:101], v[178:181], v[202:205], v[98:101]
	v_mfma_f32_16x16x32_bf16 v[114:117], v[174:177], v[182:185], v[114:117]
	v_mfma_f32_16x16x32_bf16 v[114:117], v[178:181], v[194:197], v[114:117]
	s_setprio 0
	s_barrier
	s_add_i32 s45, s45, s9
	v_lshl_add_u64 v[140:141], s[26:27], 0, v[0:1]
	s_mov_b32 m0, s45
	ds_read_b128 v[182:185], v149 offset:16384
	ds_read_b128 v[194:197], v149 offset:17408
	ds_read_b128 v[198:201], v149 offset:18432
	ds_read_b128 v[202:205], v149 offset:19456
	ds_read_b128 v[206:209], v149 offset:20480
	ds_read_b128 v[210:213], v149 offset:21504
	ds_read_b128 v[214:217], v149 offset:22528
	ds_read_b128 v[218:221], v149 offset:23552
	global_load_lds_dwordx4 v[140:141], off
	s_add_i32 m0, s45, 0x2000
	s_add_u32 s48, s26, 0x80000
	v_lshl_add_u64 v[186:187], s[26:27], 0, v[130:131]
	s_addc_u32 s49, s27, 0
	s_add_i32 s45, s47, s9
	global_load_lds_dwordx4 v[186:187], off
	v_lshl_add_u64 v[188:189], s[48:49], 0, v[0:1]
	s_mov_b32 m0, s45
	v_lshl_add_u64 v[190:191], s[28:29], 0, v[132:133]
	global_load_lds_dwordx4 v[188:189], off
	v_lshl_add_u64 v[188:189], s[48:49], 0, v[130:131]
	s_add_i32 m0, s45, 0x2000
	s_nop 0
	global_load_lds_dwordx4 v[188:189], off
	v_lshl_add_u64 v[188:189], s[28:29], 0, v[134:135]
	s_mov_b32 m0, s30
	s_nop 0
	global_load_lds_dwordx4 v[188:189], off
	s_mov_b32 m0, s31
	s_nop 0
	global_load_lds_dwordx4 v[190:191], off
	s_waitcnt vmcnt(8)
	s_waitcnt lgkmcnt(0)
	s_barrier
; #define PG8_STAGE(bufoff, gbase, voff) do { _Pragma("unroll") for (int _i = 0; _i < 2; ++_i) \
;         __builtin_amdgcn_global_load_lds((const unsigned*)((const char*)(gbase) + (voff)[_i]), (LAS unsigned*)(lds + (bufoff) + ldsw + _i * 8192), 16, 0, 0); } while (0)
; #define PG8_LDA(dst, b, h) do { _Pragma("unroll") for (int m = 0; m < 4; ++m) _Pragma("unroll") for (int k = 0; k < 2; ++k) dst[m][k] = *(const LAS bf16x8*)(lds + PG8_SA(b, h) + aoff + m * 2048 + k * 1024); } while (0)
; #define PG8_LDB(dst, b, h) do { _Pragma("unroll") for (int n = 0; n < 2; ++n) _Pragma("unroll") for (int k = 0; k < 2; ++k) dst[n][k] = *(const LAS bf16x8*)(lds + PG8_SB(b, h) + boff + n * 2048 + k * 1024); } while (0)
; #define PG8_MMA(ai, bj, At, Bt) do { __builtin_amdgcn_s_setprio(1); _Pragma("unroll") for (int m = 0; m < 4; ++m) _Pragma("unroll") for (int n = 0; n < 2; ++n) _Pragma("unroll") for (int k = 0; k < 2; ++k) \
;         acc[ai][bj][m][n] = __builtin_amdgcn_mfma_f32_16x16x32_bf16(Bt[n][k], At[m][k], acc[ai][bj][m][n], 0, 0, 0); __builtin_amdgcn_s_setprio(0); } while (0)
; #define PG8_WAIT_V(n) asm volatile("s_waitcnt vmcnt(" #n ")" ::: "memory")
; #define PG8_WAIT_L(n) asm volatile("s_waitcnt lgkmcnt(" #n ")" ::: "memory")
; #define PG8_BAR __builtin_amdgcn_s_barrier()
; #define PG8_SCHED __builtin_amdgcn_sched_barrier(0)
; template <class Epi, class Sched, bool ALIGN_EPI = false, bool SP2 = false>
; __device__ __forceinline__ void gemm_phase(LAS unsigned char* lds, const Gemm g, const Sched& S, const Epi& E) {
;     ...
;             PG8_WAIT_V(8); PG8_WAIT_L(0); PG8_BAR; PG8_MMA(1, 0, At, B0); PG8_MMA(1, 1, At, B1); PG8_BAR; PG8_SCHED;
;             PG8_LDB(B0, 1, 0); PG8_LDB(B1, 1, 1); PG8_SCHED; PG8_LDA(At, 1, 0); PG8_STAGE(PG8_SA(0, 1), a2 + hstep, voffA);
;             PG8_WAIT_V(8); PG8_WAIT_L(0); PG8_BAR; PG8_MMA(0, 0, At, B0); PG8_MMA(0, 1, At, B1); PG8_BAR; PG8_SCHED;
	s_setprio 1
	s_waitcnt lgkmcnt(0)
	v_mfma_f32_16x16x32_bf16 v[62:65], v[150:153], v[182:185], v[62:65]
	v_mfma_f32_16x16x32_bf16 v[62:65], v[154:157], v[194:197], v[62:65]
	v_mfma_f32_16x16x32_bf16 v[46:49], v[150:153], v[198:201], v[46:49]
	v_mfma_f32_16x16x32_bf16 v[46:49], v[154:157], v[202:205], v[46:49]
	v_mfma_f32_16x16x32_bf16 v[30:33], v[150:153], v[206:209], v[30:33]
	v_mfma_f32_16x16x32_bf16 v[30:33], v[154:157], v[210:213], v[30:33]
	v_mfma_f32_16x16x32_bf16 v[14:17], v[150:153], v[214:217], v[14:17]
	v_mfma_f32_16x16x32_bf16 v[14:17], v[154:157], v[218:221], v[14:17]
	v_mfma_f32_16x16x32_bf16 v[10:13], v[158:161], v[214:217], v[10:13]
	v_mfma_f32_16x16x32_bf16 v[10:13], v[162:165], v[218:221], v[10:13]
	v_mfma_f32_16x16x32_bf16 v[26:29], v[158:161], v[206:209], v[26:29]
	v_mfma_f32_16x16x32_bf16 v[26:29], v[162:165], v[210:213], v[26:29]
	v_mfma_f32_16x16x32_bf16 v[42:45], v[158:161], v[198:201], v[42:45]
	v_mfma_f32_16x16x32_bf16 v[42:45], v[162:165], v[202:205], v[42:45]
	v_mfma_f32_16x16x32_bf16 v[58:61], v[158:161], v[182:185], v[58:61]
	v_mfma_f32_16x16x32_bf16 v[58:61], v[162:165], v[194:197], v[58:61]
	s_setprio 0
	s_setprio 1
	v_mfma_f32_16x16x32_bf16 v[54:57], v[166:169], v[182:185], v[54:57]
	v_mfma_f32_16x16x32_bf16 v[54:57], v[170:173], v[194:197], v[54:57]
	v_mfma_f32_16x16x32_bf16 v[38:41], v[166:169], v[198:201], v[38:41]
	v_mfma_f32_16x16x32_bf16 v[38:41], v[170:173], v[202:205], v[38:41]
	v_mfma_f32_16x16x32_bf16 v[22:25], v[166:169], v[206:209], v[22:25]
	v_mfma_f32_16x16x32_bf16 v[22:25], v[170:173], v[210:213], v[22:25]
	v_mfma_f32_16x16x32_bf16 v[6:9], v[166:169], v[214:217], v[6:9]
	v_mfma_f32_16x16x32_bf16 v[6:9], v[170:173], v[218:221], v[6:9]
	v_mfma_f32_16x16x32_bf16 v[2:5], v[174:177], v[214:217], v[2:5]
	v_mfma_f32_16x16x32_bf16 v[2:5], v[178:181], v[218:221], v[2:5]
	v_mfma_f32_16x16x32_bf16 v[18:21], v[174:177], v[206:209], v[18:21]
	v_mfma_f32_16x16x32_bf16 v[18:21], v[178:181], v[210:213], v[18:21]
	v_mfma_f32_16x16x32_bf16 v[34:37], v[174:177], v[198:201], v[34:37]
	v_mfma_f32_16x16x32_bf16 v[34:37], v[178:181], v[202:205], v[34:37]
	v_mfma_f32_16x16x32_bf16 v[50:53], v[174:177], v[182:185], v[50:53]
	v_mfma_f32_16x16x32_bf16 v[50:53], v[178:181], v[194:197], v[50:53]
	s_setprio 0
	s_barrier
	s_add_i32 s45, 0, 0x18000
	v_add_u32_e32 v142, s45, v145
	s_add_i32 s47, 0, 0x1c000
	ds_read_b128 v[150:153], v142
	ds_read_b128 v[154:157], v142 offset:1024
	ds_read_b128 v[158:161], v142 offset:2048
	ds_read_b128 v[162:165], v142 offset:3072
	v_add_u32_e32 v142, s47, v145
	ds_read_b128 v[166:169], v142
	ds_read_b128 v[170:173], v142 offset:1024
	ds_read_b128 v[174:177], v142 offset:2048
	ds_read_b128 v[178:181], v142 offset:3072
	s_add_u32 s28, s28, 0x80000
	s_addc_u32 s29, s29, 0
	s_mov_b32 m0, s38
	v_lshl_add_u64 v[192:193], s[28:29], 0, v[134:135]
	ds_read_b128 v[182:185], v149 offset:32768
	ds_read_b128 v[194:197], v149 offset:33792
	ds_read_b128 v[198:201], v149 offset:34816
	ds_read_b128 v[202:205], v149 offset:35840
	ds_read_b128 v[206:209], v149 offset:36864
	ds_read_b128 v[210:213], v149 offset:37888
	ds_read_b128 v[214:217], v149 offset:38912
	ds_read_b128 v[218:221], v149 offset:39936
	global_load_lds_dwordx4 v[192:193], off
	v_lshl_add_u64 v[192:193], s[28:29], 0, v[132:133]
	s_mov_b32 m0, s39
	s_nop 0
	global_load_lds_dwordx4 v[192:193], off
	s_waitcnt vmcnt(8)
	s_waitcnt lgkmcnt(0)
	s_barrier
	s_setprio 1
	s_waitcnt lgkmcnt(0)
	v_mfma_f32_16x16x32_bf16 v[126:129], v[150:153], v[182:185], v[126:129]
	v_mfma_f32_16x16x32_bf16 v[126:129], v[154:157], v[194:197], v[126:129]
	v_mfma_f32_16x16x32_bf16 v[110:113], v[150:153], v[198:201], v[110:113]
	v_mfma_f32_16x16x32_bf16 v[110:113], v[154:157], v[202:205], v[110:113]
	v_mfma_f32_16x16x32_bf16 v[94:97], v[150:153], v[206:209], v[94:97]
	v_mfma_f32_16x16x32_bf16 v[94:97], v[154:157], v[210:213], v[94:97]
	v_mfma_f32_16x16x32_bf16 v[78:81], v[150:153], v[214:217], v[78:81]
	v_mfma_f32_16x16x32_bf16 v[78:81], v[154:157], v[218:221], v[78:81]
	v_mfma_f32_16x16x32_bf16 v[74:77], v[158:161], v[214:217], v[74:77]
	v_mfma_f32_16x16x32_bf16 v[74:77], v[162:165], v[218:221], v[74:77]
	v_mfma_f32_16x16x32_bf16 v[90:93], v[158:161], v[206:209], v[90:93]
	v_mfma_f32_16x16x32_bf16 v[90:93], v[162:165], v[210:213], v[90:93]
	v_mfma_f32_16x16x32_bf16 v[106:109], v[158:161], v[198:201], v[106:109]
	v_mfma_f32_16x16x32_bf16 v[106:109], v[162:165], v[202:205], v[106:109]
	v_mfma_f32_16x16x32_bf16 v[122:125], v[158:161], v[182:185], v[122:125]
	v_mfma_f32_16x16x32_bf16 v[122:125], v[162:165], v[194:197], v[122:125]
	s_setprio 0
	s_setprio 1
	v_mfma_f32_16x16x32_bf16 v[118:121], v[166:169], v[182:185], v[118:121]
	v_mfma_f32_16x16x32_bf16 v[118:121], v[170:173], v[194:197], v[118:121]
	v_mfma_f32_16x16x32_bf16 v[102:105], v[166:169], v[198:201], v[102:105]
	v_mfma_f32_16x16x32_bf16 v[102:105], v[170:173], v[202:205], v[102:105]
	v_mfma_f32_16x16x32_bf16 v[86:89], v[166:169], v[206:209], v[86:89]
	v_mfma_f32_16x16x32_bf16 v[86:89], v[170:173], v[210:213], v[86:89]
	v_mfma_f32_16x16x32_bf16 v[70:73], v[166:169], v[214:217], v[70:73]
	v_mfma_f32_16x16x32_bf16 v[70:73], v[170:173], v[218:221], v[70:73]
	v_mfma_f32_16x16x32_bf16 v[66:69], v[174:177], v[214:217], v[66:69]
	v_mfma_f32_16x16x32_bf16 v[66:69], v[178:181], v[218:221], v[66:69]
	v_mfma_f32_16x16x32_bf16 v[82:85], v[174:177], v[206:209], v[82:85]
	v_mfma_f32_16x16x32_bf16 v[82:85], v[178:181], v[210:213], v[82:85]
	v_mfma_f32_16x16x32_bf16 v[98:101], v[174:177], v[198:201], v[98:101]
	v_mfma_f32_16x16x32_bf16 v[98:101], v[178:181], v[202:205], v[98:101]
	v_mfma_f32_16x16x32_bf16 v[114:117], v[174:177], v[182:185], v[114:117]
	v_mfma_f32_16x16x32_bf16 v[114:117], v[178:181], v[194:197], v[114:117]
	s_setprio 0
	s_barrier
; #define PG8_STAGE(bufoff, gbase, voff) do { _Pragma("unroll") for (int _i = 0; _i < 2; ++_i) \
;         __builtin_amdgcn_global_load_lds((const unsigned*)((const char*)(gbase) + (voff)[_i]), (LAS unsigned*)(lds + (bufoff) + ldsw + _i * 8192), 16, 0, 0); } while (0)
; #define PG8_LDA(dst, b, h) do { _Pragma("unroll") for (int m = 0; m < 4; ++m) _Pragma("unroll") for (int k = 0; k < 2; ++k) dst[m][k] = *(const LAS bf16x8*)(lds + PG8_SA(b, h) + aoff + m * 2048 + k * 1024); } while (0)
; #define PG8_MMA(ai, bj, At, Bt) do { __builtin_amdgcn_s_setprio(1); _Pragma("unroll") for (int m = 0; m < 4; ++m) _Pragma("unroll") for (int n = 0; n < 2; ++n) _Pragma("unroll") for (int k = 0; k < 2; ++k) \
;         acc[ai][bj][m][n] = __builtin_amdgcn_mfma_f32_16x16x32_bf16(Bt[n][k], At[m][k], acc[ai][bj][m][n], 0, 0, 0); __builtin_amdgcn_s_setprio(0); } while (0)
; #define PG8_WAIT_V(n) asm volatile("s_waitcnt vmcnt(" #n ")" ::: "memory")
; #define PG8_WAIT_L(n) asm volatile("s_waitcnt lgkmcnt(" #n ")" ::: "memory")
; #define PG8_BAR __builtin_amdgcn_s_barrier()
; #define PG8_SCHED __builtin_amdgcn_sched_barrier(0)
; template <class Epi, class Sched, bool ALIGN_EPI = false, bool SP2 = false>
; __device__ __forceinline__ void gemm_phase(LAS unsigned char* lds, const Gemm g, const Sched& S, const Epi& E) {
;     ...
;             PG8_LDA(At, 1, 1); PG8_STAGE(PG8_SB(1, 0), b3, voffB); PG8_STAGE(PG8_SB(1, 1), b3 + hstep, voffB); PG8_STAGE(PG8_SA(1, 0), a3, voffA);
;             PG8_WAIT_V(8); PG8_WAIT_L(0); PG8_BAR; PG8_MMA(1, 0, At, B0); PG8_MMA(1, 1, At, B1); PG8_BAR; PG8_SCHED;
;     ...
;         if constexpr (ALIGN_EPI) { if (wr == 0) PG8_BAR; }
	s_add_i32 s28, s45, s9
	v_lshl_add_u64 v[140:141], v[140:141], 0, s[12:13]
	s_mov_b32 m0, s28
	ds_read_b128 v[182:185], v149 offset:49152
	ds_read_b128 v[194:197], v149 offset:50176
	ds_read_b128 v[198:201], v149 offset:51200
	ds_read_b128 v[202:205], v149 offset:52224
	ds_read_b128 v[206:209], v149 offset:53248
	ds_read_b128 v[210:213], v149 offset:54272
	ds_read_b128 v[214:217], v149 offset:55296
	ds_read_b128 v[218:221], v149 offset:56320
	global_load_lds_dwordx4 v[140:141], off
	s_add_i32 m0, s28, 0x2000
	s_add_u32 s26, s26, 0x80080
	v_lshl_add_u64 v[140:141], v[186:187], 0, s[12:13]
	s_addc_u32 s27, s27, 0
	s_add_i32 s28, s47, s9
	global_load_lds_dwordx4 v[140:141], off
	v_lshl_add_u64 v[140:141], s[26:27], 0, v[0:1]
	s_mov_b32 m0, s28
	s_nop 0
	global_load_lds_dwordx4 v[140:141], off
	v_lshl_add_u64 v[140:141], s[26:27], 0, v[130:131]
	s_add_i32 m0, s28, 0x2000
	s_nop 0
	global_load_lds_dwordx4 v[140:141], off
	v_lshl_add_u64 v[140:141], v[188:189], 0, s[12:13]
	s_mov_b32 m0, s40
	s_nop 0
	global_load_lds_dwordx4 v[140:141], off
	v_lshl_add_u64 v[140:141], v[190:191], 0, s[12:13]
	s_mov_b32 m0, s41
	s_nop 0
	global_load_lds_dwordx4 v[140:141], off
	s_waitcnt vmcnt(8)
	s_waitcnt lgkmcnt(0)
	s_barrier
	s_setprio 1
	s_waitcnt lgkmcnt(0)
	v_mfma_f32_16x16x32_bf16 v[62:65], v[150:153], v[182:185], v[62:65]
	v_mfma_f32_16x16x32_bf16 v[62:65], v[154:157], v[194:197], v[62:65]
	v_mfma_f32_16x16x32_bf16 v[46:49], v[150:153], v[198:201], v[46:49]
	v_mfma_f32_16x16x32_bf16 v[46:49], v[154:157], v[202:205], v[46:49]
	v_mfma_f32_16x16x32_bf16 v[30:33], v[150:153], v[206:209], v[30:33]
	v_mfma_f32_16x16x32_bf16 v[30:33], v[154:157], v[210:213], v[30:33]
	v_mfma_f32_16x16x32_bf16 v[14:17], v[150:153], v[214:217], v[14:17]
	v_mfma_f32_16x16x32_bf16 v[14:17], v[154:157], v[218:221], v[14:17]
	v_mfma_f32_16x16x32_bf16 v[10:13], v[158:161], v[214:217], v[10:13]
	v_mfma_f32_16x16x32_bf16 v[10:13], v[162:165], v[218:221], v[10:13]
	v_mfma_f32_16x16x32_bf16 v[26:29], v[158:161], v[206:209], v[26:29]
	v_mfma_f32_16x16x32_bf16 v[26:29], v[162:165], v[210:213], v[26:29]
	v_mfma_f32_16x16x32_bf16 v[42:45], v[158:161], v[198:201], v[42:45]
	v_mfma_f32_16x16x32_bf16 v[42:45], v[162:165], v[202:205], v[42:45]
	v_mfma_f32_16x16x32_bf16 v[58:61], v[158:161], v[182:185], v[58:61]
	v_mfma_f32_16x16x32_bf16 v[58:61], v[162:165], v[194:197], v[58:61]
	s_setprio 0
	s_setprio 1
	v_mfma_f32_16x16x32_bf16 v[54:57], v[166:169], v[182:185], v[54:57]
	v_mfma_f32_16x16x32_bf16 v[54:57], v[170:173], v[194:197], v[54:57]
	v_mfma_f32_16x16x32_bf16 v[38:41], v[166:169], v[198:201], v[38:41]
	v_mfma_f32_16x16x32_bf16 v[38:41], v[170:173], v[202:205], v[38:41]
	v_mfma_f32_16x16x32_bf16 v[22:25], v[166:169], v[206:209], v[22:25]
	v_mfma_f32_16x16x32_bf16 v[22:25], v[170:173], v[210:213], v[22:25]
	v_mfma_f32_16x16x32_bf16 v[6:9], v[166:169], v[214:217], v[6:9]
	v_mfma_f32_16x16x32_bf16 v[6:9], v[170:173], v[218:221], v[6:9]
	v_mfma_f32_16x16x32_bf16 v[2:5], v[174:177], v[214:217], v[2:5]
	v_mfma_f32_16x16x32_bf16 v[2:5], v[178:181], v[218:221], v[2:5]
	v_mfma_f32_16x16x32_bf16 v[18:21], v[174:177], v[206:209], v[18:21]
	v_mfma_f32_16x16x32_bf16 v[18:21], v[178:181], v[210:213], v[18:21]
	v_mfma_f32_16x16x32_bf16 v[34:37], v[174:177], v[198:201], v[34:37]
	v_mfma_f32_16x16x32_bf16 v[34:37], v[178:181], v[202:205], v[34:37]
	v_mfma_f32_16x16x32_bf16 v[50:53], v[174:177], v[182:185], v[50:53]
	v_mfma_f32_16x16x32_bf16 v[50:53], v[178:181], v[194:197], v[50:53]
	s_setprio 0
	s_barrier
	s_add_i32 s44, s44, 2
	s_add_u32 s24, s24, 0x100
	s_addc_u32 s25, s25, 0
	s_add_u32 s35, s35, 0x100
	s_addc_u32 s43, s43, 0
	s_cmp_gt_u32 s44, 29
	s_cbranch_scc0 .LBB0_173
	s_and_b64 vcc, exec, s[4:5]
	s_cbranch_vccz .LBB0_176
	s_barrier

; #define PG8_STAGE(bufoff, gbase, voff) do { _Pragma("unroll") for (int _i = 0; _i < 2; ++_i) \
;         __builtin_amdgcn_global_load_lds((const unsigned*)((const char*)(gbase) + (voff)[_i]), (LAS unsigned*)(lds + (bufoff) + ldsw + _i * 8192), 16, 0, 0); } while (0)
; #define PG8_LDA(dst, b, h) do { _Pragma("unroll") for (int m = 0; m < 4; ++m) _Pragma("unroll") for (int k = 0; k < 2; ++k) dst[m][k] = *(const LAS bf16x8*)(lds + PG8_SA(b, h) + aoff + m * 2048 + k * 1024); } while (0)
; #define PG8_LDB(dst, b, h) do { _Pragma("unroll") for (int n = 0; n < 2; ++n) _Pragma("unroll") for (int k = 0; k < 2; ++k) dst[n][k] = *(const LAS bf16x8*)(lds + PG8_SB(b, h) + boff + n * 2048 + k * 1024); } while (0)
; #define PG8_MMA(ai, bj, At, Bt) do { __builtin_amdgcn_s_setprio(1); _Pragma("unroll") for (int m = 0; m < 4; ++m) _Pragma("unroll") for (int n = 0; n < 2; ++n) _Pragma("unroll") for (int k = 0; k < 2; ++k) \
;         acc[ai][bj][m][n] = __builtin_amdgcn_mfma_f32_16x16x32_bf16(Bt[n][k], At[m][k], acc[ai][bj][m][n], 0, 0, 0); __builtin_amdgcn_s_setprio(0); } while (0)
; #define PG8_WAIT_V(n) asm volatile("s_waitcnt vmcnt(" #n ")" ::: "memory")
; #define PG8_WAIT_L(n) asm volatile("s_waitcnt lgkmcnt(" #n ")" ::: "memory")
; #define PG8_BAR __builtin_amdgcn_s_barrier()
; template <class Epi, class Sched, bool ALIGN_EPI = false, bool SP2 = false>
; __device__ __forceinline__ void gemm_phase(LAS unsigned char* lds, const Gemm g, const Sched& S, const Epi& E) {
;     ...
;             const bool last = (t == nt - 2);
;             const char* a1 = cA + (size_t)(t + 1) * kstep;
;             const char* a2 = last ? nA : cA + (size_t)(t + 2) * kstep; const char* b2 = last ? nB : cB + (size_t)(t + 2) * kstep;
;             const char* a3 = a2 + kstep; const char* b3 = b2 + kstep;
;             if (last && has_next) S.a_ready(nxt);
;             if constexpr (SP2) {
;             PG8_LDB(B0, 0, 0); PG8_LDB(B1, 0, 1); PG8_SCHED; PG8_LDA(At, 0, 0); PG8_STAGE(PG8_SA(1, 1), a1 + hstep, voffA);
;             PG8_WAIT_V(8); PG8_WAIT_L(0); PG8_BAR; PG8_MMA(0, 0, At, B0); PG8_MMA(0, 1, At, B1); PG8_BAR; PG8_SCHED;
;             PG8_LDA(At, 0, 1); PG8_STAGE(PG8_SB(0, 0), b2, voffB); PG8_STAGE(PG8_SB(0, 1), b2 + hstep, voffB); PG8_STAGE(PG8_SA(0, 0), a2, voffA);
;             PG8_WAIT_V(8); PG8_WAIT_L(0); PG8_BAR; PG8_MMA(1, 0, At, B0); PG8_MMA(1, 1, At, B1); PG8_BAR; PG8_SCHED;
.LBB0_257:
	s_add_u32 s24, s22, 0x100
	s_addc_u32 s25, s23, 0
	s_add_i32 s50, 0, 0x10000
	s_cmpk_eq_i32 s49, 0x54
	s_cselect_b32 s29, s1, s25
	s_cselect_b32 s28, s0, s24
	s_cselect_b32 s27, s21, s48
	s_cselect_b32 s26, s20, s47
	s_add_i32 s51, 0, 0x14000
	v_add_u32_e32 v126, s50, v247
	v_add_u32_e32 v158, s51, v247
	ds_read_b128 v[90:93], v126
	ds_read_b128 v[102:105], v126 offset:1024
	ds_read_b128 v[114:117], v126 offset:2048
	ds_read_b128 v[126:129], v126 offset:3072
	ds_read_b128 v[138:141], v158
	ds_read_b128 v[142:145], v158 offset:1024
	ds_read_b128 v[154:157], v158 offset:2048
	ds_read_b128 v[158:161], v158 offset:3072
	v_lshl_add_u64 v[186:187], s[22:23], 0, v[200:201]
	s_add_i32 m0, s6, 0xc000
	ds_read_b128 v[162:165], v249
	ds_read_b128 v[166:169], v249 offset:1024
	ds_read_b128 v[170:173], v249 offset:2048
	ds_read_b128 v[174:177], v249 offset:3072
	ds_read_b128 v[178:181], v249 offset:4096
	ds_read_b128 v[182:185], v249 offset:5120
	ds_read_b128 v[204:207], v249 offset:6144
	ds_read_b128 v[208:211], v249 offset:7168
	global_load_lds_dwordx4 v[186:187], off
	v_lshl_add_u64 v[186:187], s[22:23], 0, v[202:203]
	s_add_i32 m0, s6, 0xe000
	s_nop 0
	global_load_lds_dwordx4 v[186:187], off
	s_waitcnt vmcnt(8)
	s_waitcnt lgkmcnt(0)
	s_barrier
	s_setprio 1
	s_waitcnt lgkmcnt(0)
	v_mfma_f32_16x16x32_bf16 v[150:153], v[90:93], v[162:165], v[150:153]
	v_mfma_f32_16x16x32_bf16 v[150:153], v[102:105], v[166:169], v[150:153]
	v_mfma_f32_16x16x32_bf16 v[122:125], v[90:93], v[170:173], v[122:125]
	v_mfma_f32_16x16x32_bf16 v[122:125], v[102:105], v[174:177], v[122:125]
	v_mfma_f32_16x16x32_bf16 v[98:101], v[90:93], v[178:181], v[98:101]
	v_mfma_f32_16x16x32_bf16 v[98:101], v[102:105], v[182:185], v[98:101]
	v_mfma_f32_16x16x32_bf16 v[78:81], v[90:93], v[204:207], v[78:81]
	v_mfma_f32_16x16x32_bf16 v[78:81], v[102:105], v[208:211], v[78:81]
	v_mfma_f32_16x16x32_bf16 v[74:77], v[114:117], v[204:207], v[74:77]
	v_mfma_f32_16x16x32_bf16 v[74:77], v[126:129], v[208:211], v[74:77]
	v_mfma_f32_16x16x32_bf16 v[94:97], v[114:117], v[178:181], v[94:97]
	v_mfma_f32_16x16x32_bf16 v[94:97], v[126:129], v[182:185], v[94:97]
	v_mfma_f32_16x16x32_bf16 v[118:121], v[114:117], v[170:173], v[118:121]
	v_mfma_f32_16x16x32_bf16 v[118:121], v[126:129], v[174:177], v[118:121]
	v_mfma_f32_16x16x32_bf16 v[146:149], v[114:117], v[162:165], v[146:149]
	v_mfma_f32_16x16x32_bf16 v[146:149], v[126:129], v[166:169], v[146:149]
	s_setprio 0
	s_setprio 1
	v_mfma_f32_16x16x32_bf16 v[134:137], v[138:141], v[162:165], v[134:137]
	v_mfma_f32_16x16x32_bf16 v[134:137], v[142:145], v[166:169], v[134:137]
	v_mfma_f32_16x16x32_bf16 v[110:113], v[138:141], v[170:173], v[110:113]
	v_mfma_f32_16x16x32_bf16 v[110:113], v[142:145], v[174:177], v[110:113]
	v_mfma_f32_16x16x32_bf16 v[86:89], v[138:141], v[178:181], v[86:89]
	v_mfma_f32_16x16x32_bf16 v[86:89], v[142:145], v[182:185], v[86:89]
	v_mfma_f32_16x16x32_bf16 v[70:73], v[138:141], v[204:207], v[70:73]
	v_mfma_f32_16x16x32_bf16 v[70:73], v[142:145], v[208:211], v[70:73]
	v_mfma_f32_16x16x32_bf16 v[66:69], v[154:157], v[204:207], v[66:69]
	v_mfma_f32_16x16x32_bf16 v[66:69], v[158:161], v[208:211], v[66:69]
	v_mfma_f32_16x16x32_bf16 v[82:85], v[154:157], v[178:181], v[82:85]
	v_mfma_f32_16x16x32_bf16 v[82:85], v[158:161], v[182:185], v[82:85]
	v_mfma_f32_16x16x32_bf16 v[106:109], v[154:157], v[170:173], v[106:109]
	v_mfma_f32_16x16x32_bf16 v[106:109], v[158:161], v[174:177], v[106:109]
	v_mfma_f32_16x16x32_bf16 v[130:133], v[154:157], v[162:165], v[130:133]
	v_mfma_f32_16x16x32_bf16 v[130:133], v[158:161], v[166:169], v[130:133]
	s_setprio 0
	s_barrier
	s_add_i32 s22, s50, s2
	v_lshl_add_u64 v[186:187], s[26:27], 0, v[0:1]
	s_mov_b32 m0, s22
	ds_read_b128 v[162:165], v249 offset:16384
	ds_read_b128 v[166:169], v249 offset:17408
	ds_read_b128 v[170:173], v249 offset:18432
	ds_read_b128 v[174:177], v249 offset:19456
	ds_read_b128 v[178:181], v249 offset:20480
	ds_read_b128 v[182:185], v249 offset:21504
	ds_read_b128 v[204:207], v249 offset:22528
	ds_read_b128 v[208:211], v249 offset:23552
	global_load_lds_dwordx4 v[186:187], off
	s_add_i32 m0, s22, 0x2000
	s_add_u32 s22, s26, 0x160000
	v_lshl_add_u64 v[188:189], s[26:27], 0, v[194:195]
	s_addc_u32 s23, s27, 0
	s_add_i32 s50, s51, s2
	global_load_lds_dwordx4 v[188:189], off
	v_lshl_add_u64 v[190:191], s[22:23], 0, v[0:1]
	s_mov_b32 m0, s50
	v_lshl_add_u64 v[192:193], s[28:29], 0, v[196:197]
	global_load_lds_dwordx4 v[190:191], off
	v_lshl_add_u64 v[190:191], s[22:23], 0, v[194:195]
	s_add_i32 m0, s50, 0x2000
	s_nop 0
	global_load_lds_dwordx4 v[190:191], off
	v_lshl_add_u64 v[190:191], s[28:29], 0, v[198:199]
	s_mov_b32 m0, s6
	s_nop 0
	global_load_lds_dwordx4 v[190:191], off
	s_mov_b32 m0, s7
	s_nop 0
	global_load_lds_dwordx4 v[192:193], off
	s_waitcnt vmcnt(8)
	s_waitcnt lgkmcnt(0)
	s_barrier
; #define PG8_STAGE(bufoff, gbase, voff) do { _Pragma("unroll") for (int _i = 0; _i < 2; ++_i) \
;         __builtin_amdgcn_global_load_lds((const unsigned*)((const char*)(gbase) + (voff)[_i]), (LAS unsigned*)(lds + (bufoff) + ldsw + _i * 8192), 16, 0, 0); } while (0)
; #define PG8_LDA(dst, b, h) do { _Pragma("unroll") for (int m = 0; m < 4; ++m) _Pragma("unroll") for (int k = 0; k < 2; ++k) dst[m][k] = *(const LAS bf16x8*)(lds + PG8_SA(b, h) + aoff + m * 2048 + k * 1024); } while (0)
; #define PG8_LDB(dst, b, h) do { _Pragma("unroll") for (int n = 0; n < 2; ++n) _Pragma("unroll") for (int k = 0; k < 2; ++k) dst[n][k] = *(const LAS bf16x8*)(lds + PG8_SB(b, h) + boff + n * 2048 + k * 1024); } while (0)
; #define PG8_MMA(ai, bj, At, Bt) do { __builtin_amdgcn_s_setprio(1); _Pragma("unroll") for (int m = 0; m < 4; ++m) _Pragma("unroll") for (int n = 0; n < 2; ++n) _Pragma("unroll") for (int k = 0; k < 2; ++k) \
;         acc[ai][bj][m][n] = __builtin_amdgcn_mfma_f32_16x16x32_bf16(Bt[n][k], At[m][k], acc[ai][bj][m][n], 0, 0, 0); __builtin_amdgcn_s_setprio(0); } while (0)
; #define PG8_WAIT_V(n) asm volatile("s_waitcnt vmcnt(" #n ")" ::: "memory")
; #define PG8_WAIT_L(n) asm volatile("s_waitcnt lgkmcnt(" #n ")" ::: "memory")
; #define PG8_BAR __builtin_amdgcn_s_barrier()
; #define PG8_SCHED __builtin_amdgcn_sched_barrier(0)
; template <class Epi, class Sched, bool ALIGN_EPI = false, bool SP2 = false>
; __device__ __forceinline__ void gemm_phase(LAS unsigned char* lds, const Gemm g, const Sched& S, const Epi& E) {
;     ...
;             PG8_WAIT_V(8); PG8_WAIT_L(0); PG8_BAR; PG8_MMA(1, 0, At, B0); PG8_MMA(1, 1, At, B1); PG8_BAR; PG8_SCHED;
;             PG8_LDB(B0, 1, 0); PG8_LDB(B1, 1, 1); PG8_SCHED; PG8_LDA(At, 1, 0); PG8_STAGE(PG8_SA(0, 1), a2 + hstep, voffA);
;             PG8_WAIT_V(8); PG8_WAIT_L(0); PG8_BAR; PG8_MMA(0, 0, At, B0); PG8_MMA(0, 1, At, B1); PG8_BAR; PG8_SCHED;
	s_setprio 1
	s_waitcnt lgkmcnt(0)
	v_mfma_f32_16x16x32_bf16 v[62:65], v[90:93], v[162:165], v[62:65]
	v_mfma_f32_16x16x32_bf16 v[62:65], v[102:105], v[166:169], v[62:65]
	v_mfma_f32_16x16x32_bf16 v[46:49], v[90:93], v[170:173], v[46:49]
	v_mfma_f32_16x16x32_bf16 v[46:49], v[102:105], v[174:177], v[46:49]
	v_mfma_f32_16x16x32_bf16 v[30:33], v[90:93], v[178:181], v[30:33]
	v_mfma_f32_16x16x32_bf16 v[30:33], v[102:105], v[182:185], v[30:33]
	v_mfma_f32_16x16x32_bf16 v[14:17], v[90:93], v[204:207], v[14:17]
	v_mfma_f32_16x16x32_bf16 v[14:17], v[102:105], v[208:211], v[14:17]
	v_mfma_f32_16x16x32_bf16 v[10:13], v[114:117], v[204:207], v[10:13]
	v_mfma_f32_16x16x32_bf16 v[10:13], v[126:129], v[208:211], v[10:13]
	v_mfma_f32_16x16x32_bf16 v[26:29], v[114:117], v[178:181], v[26:29]
	v_mfma_f32_16x16x32_bf16 v[26:29], v[126:129], v[182:185], v[26:29]
	v_mfma_f32_16x16x32_bf16 v[42:45], v[114:117], v[170:173], v[42:45]
	v_mfma_f32_16x16x32_bf16 v[42:45], v[126:129], v[174:177], v[42:45]
	v_mfma_f32_16x16x32_bf16 v[58:61], v[114:117], v[162:165], v[58:61]
	v_mfma_f32_16x16x32_bf16 v[58:61], v[126:129], v[166:169], v[58:61]
	s_setprio 0
	s_setprio 1
	v_mfma_f32_16x16x32_bf16 v[54:57], v[138:141], v[162:165], v[54:57]
	v_mfma_f32_16x16x32_bf16 v[54:57], v[142:145], v[166:169], v[54:57]
	v_mfma_f32_16x16x32_bf16 v[38:41], v[138:141], v[170:173], v[38:41]
	v_mfma_f32_16x16x32_bf16 v[38:41], v[142:145], v[174:177], v[38:41]
	v_mfma_f32_16x16x32_bf16 v[22:25], v[138:141], v[178:181], v[22:25]
	v_mfma_f32_16x16x32_bf16 v[22:25], v[142:145], v[182:185], v[22:25]
	v_mfma_f32_16x16x32_bf16 v[6:9], v[138:141], v[204:207], v[6:9]
	v_mfma_f32_16x16x32_bf16 v[6:9], v[142:145], v[208:211], v[6:9]
	v_mfma_f32_16x16x32_bf16 v[2:5], v[154:157], v[204:207], v[2:5]
	v_mfma_f32_16x16x32_bf16 v[2:5], v[158:161], v[208:211], v[2:5]
	v_mfma_f32_16x16x32_bf16 v[18:21], v[154:157], v[178:181], v[18:21]
	v_mfma_f32_16x16x32_bf16 v[18:21], v[158:161], v[182:185], v[18:21]
	v_mfma_f32_16x16x32_bf16 v[34:37], v[154:157], v[170:173], v[34:37]
	v_mfma_f32_16x16x32_bf16 v[34:37], v[158:161], v[174:177], v[34:37]
	v_mfma_f32_16x16x32_bf16 v[50:53], v[154:157], v[162:165], v[50:53]
	v_mfma_f32_16x16x32_bf16 v[50:53], v[158:161], v[166:169], v[50:53]
	s_setprio 0
	s_barrier
	s_add_i32 s50, 0, 0x18000
	s_add_i32 s51, 0, 0x1c000
	v_add_u32_e32 v126, s50, v247
	v_add_u32_e32 v158, s51, v247
	ds_read_b128 v[90:93], v126
	ds_read_b128 v[102:105], v126 offset:1024
	ds_read_b128 v[114:117], v126 offset:2048
	ds_read_b128 v[126:129], v126 offset:3072
	ds_read_b128 v[138:141], v158
	ds_read_b128 v[142:145], v158 offset:1024
	ds_read_b128 v[154:157], v158 offset:2048
	ds_read_b128 v[158:161], v158 offset:3072
	s_add_u32 s22, s28, 0x160000
	s_addc_u32 s23, s29, 0
	s_mov_b32 m0, s8
	v_lshl_add_u64 v[212:213], s[22:23], 0, v[198:199]
	ds_read_b128 v[162:165], v249 offset:32768
	ds_read_b128 v[166:169], v249 offset:33792
	ds_read_b128 v[170:173], v249 offset:34816
	ds_read_b128 v[174:177], v249 offset:35840
	ds_read_b128 v[178:181], v249 offset:36864
	ds_read_b128 v[182:185], v249 offset:37888
	ds_read_b128 v[204:207], v249 offset:38912
	ds_read_b128 v[208:211], v249 offset:39936
	global_load_lds_dwordx4 v[212:213], off
	v_lshl_add_u64 v[212:213], s[22:23], 0, v[196:197]
	s_mov_b32 m0, s31
	s_nop 0
	global_load_lds_dwordx4 v[212:213], off
	s_waitcnt vmcnt(8)
	s_waitcnt lgkmcnt(0)
	s_barrier
	s_setprio 1
	s_waitcnt lgkmcnt(0)
	v_mfma_f32_16x16x32_bf16 v[150:153], v[90:93], v[162:165], v[150:153]
	v_mfma_f32_16x16x32_bf16 v[150:153], v[102:105], v[166:169], v[150:153]
	v_mfma_f32_16x16x32_bf16 v[122:125], v[90:93], v[170:173], v[122:125]
	v_mfma_f32_16x16x32_bf16 v[122:125], v[102:105], v[174:177], v[122:125]
	v_mfma_f32_16x16x32_bf16 v[98:101], v[90:93], v[178:181], v[98:101]
	v_mfma_f32_16x16x32_bf16 v[98:101], v[102:105], v[182:185], v[98:101]
	v_mfma_f32_16x16x32_bf16 v[78:81], v[90:93], v[204:207], v[78:81]
	v_mfma_f32_16x16x32_bf16 v[78:81], v[102:105], v[208:211], v[78:81]
	v_mfma_f32_16x16x32_bf16 v[74:77], v[114:117], v[204:207], v[74:77]
	v_mfma_f32_16x16x32_bf16 v[74:77], v[126:129], v[208:211], v[74:77]
	v_mfma_f32_16x16x32_bf16 v[94:97], v[114:117], v[178:181], v[94:97]
	v_mfma_f32_16x16x32_bf16 v[94:97], v[126:129], v[182:185], v[94:97]
	v_mfma_f32_16x16x32_bf16 v[118:121], v[114:117], v[170:173], v[118:121]
	v_mfma_f32_16x16x32_bf16 v[118:121], v[126:129], v[174:177], v[118:121]
	v_mfma_f32_16x16x32_bf16 v[146:149], v[114:117], v[162:165], v[146:149]
	v_mfma_f32_16x16x32_bf16 v[146:149], v[126:129], v[166:169], v[146:149]
	s_setprio 0
	s_setprio 1
	v_mfma_f32_16x16x32_bf16 v[134:137], v[138:141], v[162:165], v[134:137]
	v_mfma_f32_16x16x32_bf16 v[134:137], v[142:145], v[166:169], v[134:137]
	v_mfma_f32_16x16x32_bf16 v[110:113], v[138:141], v[170:173], v[110:113]
	v_mfma_f32_16x16x32_bf16 v[110:113], v[142:145], v[174:177], v[110:113]
	v_mfma_f32_16x16x32_bf16 v[86:89], v[138:141], v[178:181], v[86:89]
	v_mfma_f32_16x16x32_bf16 v[86:89], v[142:145], v[182:185], v[86:89]
	v_mfma_f32_16x16x32_bf16 v[70:73], v[138:141], v[204:207], v[70:73]
	v_mfma_f32_16x16x32_bf16 v[70:73], v[142:145], v[208:211], v[70:73]
	v_mfma_f32_16x16x32_bf16 v[66:69], v[154:157], v[204:207], v[66:69]
	v_mfma_f32_16x16x32_bf16 v[66:69], v[158:161], v[208:211], v[66:69]
	v_mfma_f32_16x16x32_bf16 v[82:85], v[154:157], v[178:181], v[82:85]
	v_mfma_f32_16x16x32_bf16 v[82:85], v[158:161], v[182:185], v[82:85]
	v_mfma_f32_16x16x32_bf16 v[106:109], v[154:157], v[170:173], v[106:109]
	v_mfma_f32_16x16x32_bf16 v[106:109], v[158:161], v[174:177], v[106:109]
	v_mfma_f32_16x16x32_bf16 v[130:133], v[154:157], v[162:165], v[130:133]
	v_mfma_f32_16x16x32_bf16 v[130:133], v[158:161], v[166:169], v[130:133]
	s_setprio 0
	s_barrier
; #define PG8_STAGE(bufoff, gbase, voff) do { _Pragma("unroll") for (int _i = 0; _i < 2; ++_i) \
;         __builtin_amdgcn_global_load_lds((const unsigned*)((const char*)(gbase) + (voff)[_i]), (LAS unsigned*)(lds + (bufoff) + ldsw + _i * 8192), 16, 0, 0); } while (0)
; #define PG8_LDA(dst, b, h) do { _Pragma("unroll") for (int m = 0; m < 4; ++m) _Pragma("unroll") for (int k = 0; k < 2; ++k) dst[m][k] = *(const LAS bf16x8*)(lds + PG8_SA(b, h) + aoff + m * 2048 + k * 1024); } while (0)
; #define PG8_MMA(ai, bj, At, Bt) do { __builtin_amdgcn_s_setprio(1); _Pragma("unroll") for (int m = 0; m < 4; ++m) _Pragma("unroll") for (int n = 0; n < 2; ++n) _Pragma("unroll") for (int k = 0; k < 2; ++k) \
;         acc[ai][bj][m][n] = __builtin_amdgcn_mfma_f32_16x16x32_bf16(Bt[n][k], At[m][k], acc[ai][bj][m][n], 0, 0, 0); __builtin_amdgcn_s_setprio(0); } while (0)
; #define PG8_WAIT_V(n) asm volatile("s_waitcnt vmcnt(" #n ")" ::: "memory")
; #define PG8_WAIT_L(n) asm volatile("s_waitcnt lgkmcnt(" #n ")" ::: "memory")
; #define PG8_BAR __builtin_amdgcn_s_barrier()
; #define PG8_SCHED __builtin_amdgcn_sched_barrier(0)
; template <class Epi, class Sched, bool ALIGN_EPI = false, bool SP2 = false>
; __device__ __forceinline__ void gemm_phase(LAS unsigned char* lds, const Gemm g, const Sched& S, const Epi& E) {
;     ...
;         for (int t = 0; t < nt; t += 2) {
;             const bool last = (t == nt - 2);
;             const char* a1 = cA + (size_t)(t + 1) * kstep;
;             const char* a2 = last ? nA : cA + (size_t)(t + 2) * kstep; const char* b2 = last ? nB : cB + (size_t)(t + 2) * kstep;
;     ...
;             PG8_LDA(At, 1, 1); PG8_STAGE(PG8_SB(1, 0), b3, voffB); PG8_STAGE(PG8_SB(1, 1), b3 + hstep, voffB); PG8_STAGE(PG8_SA(1, 0), a3, voffA);
;             PG8_WAIT_V(8); PG8_WAIT_L(0); PG8_BAR; PG8_MMA(1, 0, At, B0); PG8_MMA(1, 1, At, B1); PG8_BAR; PG8_SCHED;
	s_add_i32 s22, s50, s2
	v_lshl_add_u64 v[186:187], v[186:187], 0, s[12:13]
	s_mov_b32 m0, s22
	ds_read_b128 v[162:165], v249 offset:49152
	ds_read_b128 v[166:169], v249 offset:50176
	ds_read_b128 v[170:173], v249 offset:51200
	ds_read_b128 v[174:177], v249 offset:52224
	ds_read_b128 v[178:181], v249 offset:53248
	ds_read_b128 v[182:185], v249 offset:54272
	ds_read_b128 v[204:207], v249 offset:55296
	ds_read_b128 v[208:211], v249 offset:56320
	global_load_lds_dwordx4 v[186:187], off
	s_add_i32 m0, s22, 0x2000
	s_add_u32 s22, s26, 0x160080
	v_lshl_add_u64 v[186:187], v[188:189], 0, s[12:13]
	s_addc_u32 s23, s27, 0
	s_add_i32 s26, s51, s2
	global_load_lds_dwordx4 v[186:187], off
	v_lshl_add_u64 v[186:187], s[22:23], 0, v[0:1]
	s_mov_b32 m0, s26
	s_nop 0
	global_load_lds_dwordx4 v[186:187], off
	v_lshl_add_u64 v[186:187], s[22:23], 0, v[194:195]
	s_add_i32 m0, s26, 0x2000
	s_nop 0
	global_load_lds_dwordx4 v[186:187], off
	v_lshl_add_u64 v[186:187], v[190:191], 0, s[12:13]
	s_mov_b32 m0, s35
	s_nop 0
	global_load_lds_dwordx4 v[186:187], off
	v_lshl_add_u64 v[186:187], v[192:193], 0, s[12:13]
	s_mov_b32 m0, s40
	s_nop 0
	global_load_lds_dwordx4 v[186:187], off
	s_waitcnt vmcnt(8)
	s_waitcnt lgkmcnt(0)
	s_barrier
	s_setprio 1
	s_waitcnt lgkmcnt(0)
	v_mfma_f32_16x16x32_bf16 v[62:65], v[90:93], v[162:165], v[62:65]
	v_mfma_f32_16x16x32_bf16 v[62:65], v[102:105], v[166:169], v[62:65]
	v_mfma_f32_16x16x32_bf16 v[46:49], v[90:93], v[170:173], v[46:49]
	v_mfma_f32_16x16x32_bf16 v[46:49], v[102:105], v[174:177], v[46:49]
	v_mfma_f32_16x16x32_bf16 v[30:33], v[90:93], v[178:181], v[30:33]
	v_mfma_f32_16x16x32_bf16 v[30:33], v[102:105], v[182:185], v[30:33]
	v_mfma_f32_16x16x32_bf16 v[14:17], v[90:93], v[204:207], v[14:17]
	v_mfma_f32_16x16x32_bf16 v[14:17], v[102:105], v[208:211], v[14:17]
	v_mfma_f32_16x16x32_bf16 v[10:13], v[114:117], v[204:207], v[10:13]
	v_mfma_f32_16x16x32_bf16 v[10:13], v[126:129], v[208:211], v[10:13]
	v_mfma_f32_16x16x32_bf16 v[26:29], v[114:117], v[178:181], v[26:29]
	v_mfma_f32_16x16x32_bf16 v[26:29], v[126:129], v[182:185], v[26:29]
	v_mfma_f32_16x16x32_bf16 v[42:45], v[114:117], v[170:173], v[42:45]
	v_mfma_f32_16x16x32_bf16 v[42:45], v[126:129], v[174:177], v[42:45]
	v_mfma_f32_16x16x32_bf16 v[58:61], v[114:117], v[162:165], v[58:61]
	v_mfma_f32_16x16x32_bf16 v[58:61], v[126:129], v[166:169], v[58:61]
	s_setprio 0
	s_setprio 1
	v_mfma_f32_16x16x32_bf16 v[54:57], v[138:141], v[162:165], v[54:57]
	v_mfma_f32_16x16x32_bf16 v[54:57], v[142:145], v[166:169], v[54:57]
	v_mfma_f32_16x16x32_bf16 v[38:41], v[138:141], v[170:173], v[38:41]
	v_mfma_f32_16x16x32_bf16 v[38:41], v[142:145], v[174:177], v[38:41]
	v_mfma_f32_16x16x32_bf16 v[22:25], v[138:141], v[178:181], v[22:25]
	v_mfma_f32_16x16x32_bf16 v[22:25], v[142:145], v[182:185], v[22:25]
	v_mfma_f32_16x16x32_bf16 v[6:9], v[138:141], v[204:207], v[6:9]
	v_mfma_f32_16x16x32_bf16 v[6:9], v[142:145], v[208:211], v[6:9]
	v_mfma_f32_16x16x32_bf16 v[2:5], v[154:157], v[204:207], v[2:5]
	v_mfma_f32_16x16x32_bf16 v[2:5], v[158:161], v[208:211], v[2:5]
	v_mfma_f32_16x16x32_bf16 v[18:21], v[154:157], v[178:181], v[18:21]
	v_mfma_f32_16x16x32_bf16 v[18:21], v[158:161], v[182:185], v[18:21]
	v_mfma_f32_16x16x32_bf16 v[34:37], v[154:157], v[170:173], v[34:37]
	v_mfma_f32_16x16x32_bf16 v[34:37], v[158:161], v[174:177], v[34:37]
	v_mfma_f32_16x16x32_bf16 v[50:53], v[154:157], v[162:165], v[50:53]
	v_mfma_f32_16x16x32_bf16 v[50:53], v[158:161], v[166:169], v[50:53]
	s_setprio 0
	s_barrier
	s_add_i32 s49, s49, 2
	s_add_u32 s47, s47, 0x100
	s_addc_u32 s48, s48, 0
	s_cmpk_gt_u32 s49, 0x55
	s_mov_b64 s[22:23], s[24:25]
	s_cbranch_scc0 .LBB0_257
	s_and_b64 vcc, exec, s[18:19]
	s_cbranch_vccz .LBB0_260
	s_barrier

; #define PG8_STAGE(bufoff, gbase, voff) do { _Pragma("unroll") for (int _i = 0; _i < 2; ++_i) \
;         __builtin_amdgcn_global_load_lds((const unsigned*)((const char*)(gbase) + (voff)[_i]), (LAS unsigned*)(lds + (bufoff) + ldsw + _i * 8192), 16, 0, 0); } while (0)
; #define PG8_LDA(dst, b, h) do { _Pragma("unroll") for (int m = 0; m < 4; ++m) _Pragma("unroll") for (int k = 0; k < 2; ++k) dst[m][k] = *(const LAS bf16x8*)(lds + PG8_SA(b, h) + aoff + m * 2048 + k * 1024); } while (0)
; #define PG8_LDB(dst, b, h) do { _Pragma("unroll") for (int n = 0; n < 2; ++n) _Pragma("unroll") for (int k = 0; k < 2; ++k) dst[n][k] = *(const LAS bf16x8*)(lds + PG8_SB(b, h) + boff + n * 2048 + k * 1024); } while (0)
; #define PG8_MMA(ai, bj, At, Bt) do { __builtin_amdgcn_s_setprio(1); _Pragma("unroll") for (int m = 0; m < 4; ++m) _Pragma("unroll") for (int n = 0; n < 2; ++n) _Pragma("unroll") for (int k = 0; k < 2; ++k) \
;         acc[ai][bj][m][n] = __builtin_amdgcn_mfma_f32_16x16x32_bf16(Bt[n][k], At[m][k], acc[ai][bj][m][n], 0, 0, 0); __builtin_amdgcn_s_setprio(0); } while (0)
; #define PG8_WAIT_V(n) asm volatile("s_waitcnt vmcnt(" #n ")" ::: "memory")
; #define PG8_WAIT_L(n) asm volatile("s_waitcnt lgkmcnt(" #n ")" ::: "memory")
; #define PG8_BAR __builtin_amdgcn_s_barrier()
; #define PG8_SCHED __builtin_amdgcn_sched_barrier(0)
; template <class Epi, class Sched, bool ALIGN_EPI = false, bool SP2 = false>
; __device__ __forceinline__ void gemm_phase(LAS unsigned char* lds, const Gemm g, const Sched& S, const Epi& E) {
;     ...
;             PG8_LDB(B0, 0, 0); PG8_LDB(B1, 0, 1); PG8_SCHED; PG8_LDA(At, 0, 0); PG8_STAGE(PG8_SA(1, 1), a1 + hstep, voffA);
;             PG8_WAIT_V(8); PG8_WAIT_L(0); PG8_BAR; PG8_MMA(0, 0, At, B0); PG8_MMA(0, 1, At, B1); PG8_BAR; PG8_SCHED;
;             PG8_LDA(At, 0, 1); PG8_STAGE(PG8_SB(0, 0), b2, voffB); PG8_STAGE(PG8_SB(0, 1), b2 + hstep, voffB); PG8_STAGE(PG8_SA(0, 0), a2, voffA);
;             PG8_WAIT_V(8); PG8_WAIT_L(0); PG8_BAR; PG8_MMA(1, 0, At, B0); PG8_MMA(1, 1, At, B1); PG8_BAR; PG8_SCHED;
.LBB0_359:
	s_add_u32 s28, s26, 0xfff80080
	s_addc_u32 s29, s27, -1
	s_add_i32 s41, 0, 0x10000
	s_cmp_eq_u32 s40, 28
	s_cselect_b32 s31, s6, s29
	s_cselect_b32 s30, s7, s28
	v_add_u32_e32 v0, s41, v159
	s_cselect_b32 s29, s8, s35
	s_cselect_b32 s28, s19, s21
	s_add_i32 s57, 0, 0x14000
	ds_read_b128 v[142:145], v0
	ds_read_b128 v[146:149], v0 offset:1024
	ds_read_b128 v[150:153], v0 offset:2048
	ds_read_b128 v[154:157], v0 offset:3072
	v_add_u32_e32 v0, s57, v159
	ds_read_b128 v[162:165], v0
	ds_read_b128 v[166:169], v0 offset:1024
	ds_read_b128 v[170:173], v0 offset:2048
	ds_read_b128 v[174:177], v0 offset:3072
	v_lshl_add_u64 v[210:211], s[26:27], 0, v[138:139]
	s_add_i32 m0, s44, 0xc000
	ds_read_b128 v[178:181], v161
	ds_read_b128 v[182:185], v161 offset:1024
	ds_read_b128 v[186:189], v161 offset:2048
	ds_read_b128 v[190:193], v161 offset:3072
	ds_read_b128 v[194:197], v161 offset:4096
	ds_read_b128 v[198:201], v161 offset:5120
	ds_read_b128 v[202:205], v161 offset:6144
	ds_read_b128 v[206:209], v161 offset:7168
	global_load_lds_dwordx4 v[210:211], off
	v_lshl_add_u64 v[210:211], s[26:27], 0, v[140:141]
	s_add_i32 m0, s44, 0xe000
	s_nop 0
	global_load_lds_dwordx4 v[210:211], off
	s_waitcnt vmcnt(8)
	s_waitcnt lgkmcnt(0)
	s_barrier
	s_setprio 1
	s_waitcnt lgkmcnt(0)
	v_mfma_f32_16x16x32_bf16 v[126:129], v[142:145], v[178:181], v[126:129]
	v_mfma_f32_16x16x32_bf16 v[126:129], v[146:149], v[182:185], v[126:129]
	v_mfma_f32_16x16x32_bf16 v[110:113], v[142:145], v[186:189], v[110:113]
	v_mfma_f32_16x16x32_bf16 v[110:113], v[146:149], v[190:193], v[110:113]
	v_mfma_f32_16x16x32_bf16 v[94:97], v[142:145], v[194:197], v[94:97]
	v_mfma_f32_16x16x32_bf16 v[94:97], v[146:149], v[198:201], v[94:97]
	v_mfma_f32_16x16x32_bf16 v[78:81], v[142:145], v[202:205], v[78:81]
	v_mfma_f32_16x16x32_bf16 v[78:81], v[146:149], v[206:209], v[78:81]
	v_mfma_f32_16x16x32_bf16 v[74:77], v[150:153], v[202:205], v[74:77]
	v_mfma_f32_16x16x32_bf16 v[74:77], v[154:157], v[206:209], v[74:77]
	v_mfma_f32_16x16x32_bf16 v[90:93], v[150:153], v[194:197], v[90:93]
	v_mfma_f32_16x16x32_bf16 v[90:93], v[154:157], v[198:201], v[90:93]
	v_mfma_f32_16x16x32_bf16 v[106:109], v[150:153], v[186:189], v[106:109]
	v_mfma_f32_16x16x32_bf16 v[106:109], v[154:157], v[190:193], v[106:109]
	v_mfma_f32_16x16x32_bf16 v[122:125], v[150:153], v[178:181], v[122:125]
	v_mfma_f32_16x16x32_bf16 v[122:125], v[154:157], v[182:185], v[122:125]
	s_setprio 0
	s_setprio 1
	v_mfma_f32_16x16x32_bf16 v[118:121], v[162:165], v[178:181], v[118:121]
	v_mfma_f32_16x16x32_bf16 v[118:121], v[166:169], v[182:185], v[118:121]
	v_mfma_f32_16x16x32_bf16 v[102:105], v[162:165], v[186:189], v[102:105]
	v_mfma_f32_16x16x32_bf16 v[102:105], v[166:169], v[190:193], v[102:105]
	v_mfma_f32_16x16x32_bf16 v[86:89], v[162:165], v[194:197], v[86:89]
	v_mfma_f32_16x16x32_bf16 v[86:89], v[166:169], v[198:201], v[86:89]
	v_mfma_f32_16x16x32_bf16 v[70:73], v[162:165], v[202:205], v[70:73]
	v_mfma_f32_16x16x32_bf16 v[70:73], v[166:169], v[206:209], v[70:73]
	v_mfma_f32_16x16x32_bf16 v[66:69], v[170:173], v[202:205], v[66:69]
	v_mfma_f32_16x16x32_bf16 v[66:69], v[174:177], v[206:209], v[66:69]
	v_mfma_f32_16x16x32_bf16 v[82:85], v[170:173], v[194:197], v[82:85]
	v_mfma_f32_16x16x32_bf16 v[82:85], v[174:177], v[198:201], v[82:85]
	v_mfma_f32_16x16x32_bf16 v[98:101], v[170:173], v[186:189], v[98:101]
	v_mfma_f32_16x16x32_bf16 v[98:101], v[174:177], v[190:193], v[98:101]
	v_mfma_f32_16x16x32_bf16 v[114:117], v[170:173], v[178:181], v[114:117]
	v_mfma_f32_16x16x32_bf16 v[114:117], v[174:177], v[182:185], v[114:117]
	s_setprio 0
	s_barrier
	s_add_i32 s41, s41, s9
	v_lshl_add_u64 v[210:211], s[28:29], 0, v[134:135]
	s_mov_b32 m0, s41
	ds_read_b128 v[178:181], v161 offset:16384
	ds_read_b128 v[182:185], v161 offset:17408
	ds_read_b128 v[186:189], v161 offset:18432
	ds_read_b128 v[190:193], v161 offset:19456
	ds_read_b128 v[194:197], v161 offset:20480
	ds_read_b128 v[198:201], v161 offset:21504
	ds_read_b128 v[202:205], v161 offset:22528
	ds_read_b128 v[206:209], v161 offset:23552
	global_load_lds_dwordx4 v[210:211], off
	s_add_i32 m0, s41, 0x2000
	s_add_u32 s58, s28, 0x80000
	v_lshl_add_u64 v[212:213], s[28:29], 0, v[130:131]
	s_addc_u32 s59, s29, 0
	s_add_i32 s41, s57, s9
	global_load_lds_dwordx4 v[212:213], off
	v_lshl_add_u64 v[214:215], s[58:59], 0, v[134:135]
	s_mov_b32 m0, s41
	v_lshl_add_u64 v[216:217], s[30:31], 0, v[132:133]
	global_load_lds_dwordx4 v[214:215], off
	v_lshl_add_u64 v[214:215], s[58:59], 0, v[130:131]
	s_add_i32 m0, s41, 0x2000
	s_nop 0
	global_load_lds_dwordx4 v[214:215], off
	v_lshl_add_u64 v[214:215], s[30:31], 0, v[136:137]
	s_mov_b32 m0, s44
	s_nop 0
	global_load_lds_dwordx4 v[214:215], off
	s_mov_b32 m0, s45
	s_nop 0
	global_load_lds_dwordx4 v[216:217], off
	s_waitcnt vmcnt(8)
	s_waitcnt lgkmcnt(0)
	s_barrier
; #define PG8_STAGE(bufoff, gbase, voff) do { _Pragma("unroll") for (int _i = 0; _i < 2; ++_i) \
;         __builtin_amdgcn_global_load_lds((const unsigned*)((const char*)(gbase) + (voff)[_i]), (LAS unsigned*)(lds + (bufoff) + ldsw + _i * 8192), 16, 0, 0); } while (0)
; #define PG8_LDA(dst, b, h) do { _Pragma("unroll") for (int m = 0; m < 4; ++m) _Pragma("unroll") for (int k = 0; k < 2; ++k) dst[m][k] = *(const LAS bf16x8*)(lds + PG8_SA(b, h) + aoff + m * 2048 + k * 1024); } while (0)
; #define PG8_LDB(dst, b, h) do { _Pragma("unroll") for (int n = 0; n < 2; ++n) _Pragma("unroll") for (int k = 0; k < 2; ++k) dst[n][k] = *(const LAS bf16x8*)(lds + PG8_SB(b, h) + boff + n * 2048 + k * 1024); } while (0)
; #define PG8_MMA(ai, bj, At, Bt) do { __builtin_amdgcn_s_setprio(1); _Pragma("unroll") for (int m = 0; m < 4; ++m) _Pragma("unroll") for (int n = 0; n < 2; ++n) _Pragma("unroll") for (int k = 0; k < 2; ++k) \
;         acc[ai][bj][m][n] = __builtin_amdgcn_mfma_f32_16x16x32_bf16(Bt[n][k], At[m][k], acc[ai][bj][m][n], 0, 0, 0); __builtin_amdgcn_s_setprio(0); } while (0)
; #define PG8_WAIT_V(n) asm volatile("s_waitcnt vmcnt(" #n ")" ::: "memory")
; #define PG8_WAIT_L(n) asm volatile("s_waitcnt lgkmcnt(" #n ")" ::: "memory")
; #define PG8_BAR __builtin_amdgcn_s_barrier()
; #define PG8_SCHED __builtin_amdgcn_sched_barrier(0)
; template <class Epi, class Sched, bool ALIGN_EPI = false, bool SP2 = false>
; __device__ __forceinline__ void gemm_phase(LAS unsigned char* lds, const Gemm g, const Sched& S, const Epi& E) {
;     ...
;             PG8_WAIT_V(8); PG8_WAIT_L(0); PG8_BAR; PG8_MMA(1, 0, At, B0); PG8_MMA(1, 1, At, B1); PG8_BAR; PG8_SCHED;
;             PG8_LDB(B0, 1, 0); PG8_LDB(B1, 1, 1); PG8_SCHED; PG8_LDA(At, 1, 0); PG8_STAGE(PG8_SA(0, 1), a2 + hstep, voffA);
;             PG8_WAIT_V(8); PG8_WAIT_L(0); PG8_BAR; PG8_MMA(0, 0, At, B0); PG8_MMA(0, 1, At, B1); PG8_BAR; PG8_SCHED;
	s_setprio 1
	s_waitcnt lgkmcnt(0)
	v_mfma_f32_16x16x32_bf16 v[62:65], v[142:145], v[178:181], v[62:65]
	v_mfma_f32_16x16x32_bf16 v[62:65], v[146:149], v[182:185], v[62:65]
	v_mfma_f32_16x16x32_bf16 v[46:49], v[142:145], v[186:189], v[46:49]
	v_mfma_f32_16x16x32_bf16 v[46:49], v[146:149], v[190:193], v[46:49]
	v_mfma_f32_16x16x32_bf16 v[30:33], v[142:145], v[194:197], v[30:33]
	v_mfma_f32_16x16x32_bf16 v[30:33], v[146:149], v[198:201], v[30:33]
	v_mfma_f32_16x16x32_bf16 v[14:17], v[142:145], v[202:205], v[14:17]
	v_mfma_f32_16x16x32_bf16 v[14:17], v[146:149], v[206:209], v[14:17]
	v_mfma_f32_16x16x32_bf16 v[10:13], v[150:153], v[202:205], v[10:13]
	v_mfma_f32_16x16x32_bf16 v[10:13], v[154:157], v[206:209], v[10:13]
	v_mfma_f32_16x16x32_bf16 v[26:29], v[150:153], v[194:197], v[26:29]
	v_mfma_f32_16x16x32_bf16 v[26:29], v[154:157], v[198:201], v[26:29]
	v_mfma_f32_16x16x32_bf16 v[42:45], v[150:153], v[186:189], v[42:45]
	v_mfma_f32_16x16x32_bf16 v[42:45], v[154:157], v[190:193], v[42:45]
	v_mfma_f32_16x16x32_bf16 v[58:61], v[150:153], v[178:181], v[58:61]
	v_mfma_f32_16x16x32_bf16 v[58:61], v[154:157], v[182:185], v[58:61]
	s_setprio 0
	s_setprio 1
	v_mfma_f32_16x16x32_bf16 v[54:57], v[162:165], v[178:181], v[54:57]
	v_mfma_f32_16x16x32_bf16 v[54:57], v[166:169], v[182:185], v[54:57]
	v_mfma_f32_16x16x32_bf16 v[38:41], v[162:165], v[186:189], v[38:41]
	v_mfma_f32_16x16x32_bf16 v[38:41], v[166:169], v[190:193], v[38:41]
	v_mfma_f32_16x16x32_bf16 v[22:25], v[162:165], v[194:197], v[22:25]
	v_mfma_f32_16x16x32_bf16 v[22:25], v[166:169], v[198:201], v[22:25]
	v_mfma_f32_16x16x32_bf16 v[6:9], v[162:165], v[202:205], v[6:9]
	v_mfma_f32_16x16x32_bf16 v[6:9], v[166:169], v[206:209], v[6:9]
	v_mfma_f32_16x16x32_bf16 v[2:5], v[170:173], v[202:205], v[2:5]
	v_mfma_f32_16x16x32_bf16 v[2:5], v[174:177], v[206:209], v[2:5]
	v_mfma_f32_16x16x32_bf16 v[18:21], v[170:173], v[194:197], v[18:21]
	v_mfma_f32_16x16x32_bf16 v[18:21], v[174:177], v[198:201], v[18:21]
	v_mfma_f32_16x16x32_bf16 v[34:37], v[170:173], v[186:189], v[34:37]
	v_mfma_f32_16x16x32_bf16 v[34:37], v[174:177], v[190:193], v[34:37]
	v_mfma_f32_16x16x32_bf16 v[50:53], v[170:173], v[178:181], v[50:53]
	v_mfma_f32_16x16x32_bf16 v[50:53], v[174:177], v[182:185], v[50:53]
	s_setprio 0
	s_barrier
	s_add_i32 s41, 0, 0x18000
	v_add_u32_e32 v0, s41, v159
	s_add_i32 s57, 0, 0x1c000
	ds_read_b128 v[142:145], v0
	ds_read_b128 v[146:149], v0 offset:1024
	ds_read_b128 v[150:153], v0 offset:2048
	ds_read_b128 v[154:157], v0 offset:3072
	v_add_u32_e32 v0, s57, v159
	ds_read_b128 v[162:165], v0
	ds_read_b128 v[166:169], v0 offset:1024
	ds_read_b128 v[170:173], v0 offset:2048
	ds_read_b128 v[174:177], v0 offset:3072
	s_add_u32 s30, s30, 0x80000
	s_addc_u32 s31, s31, 0
	s_mov_b32 m0, s47
	v_lshl_add_u64 v[218:219], s[30:31], 0, v[136:137]
	ds_read_b128 v[178:181], v161 offset:32768
	ds_read_b128 v[182:185], v161 offset:33792
	ds_read_b128 v[186:189], v161 offset:34816
	ds_read_b128 v[190:193], v161 offset:35840
	ds_read_b128 v[194:197], v161 offset:36864
	ds_read_b128 v[198:201], v161 offset:37888
	ds_read_b128 v[202:205], v161 offset:38912
	ds_read_b128 v[206:209], v161 offset:39936
	global_load_lds_dwordx4 v[218:219], off
	v_lshl_add_u64 v[218:219], s[30:31], 0, v[132:133]
	s_mov_b32 m0, s48
	s_nop 0
	global_load_lds_dwordx4 v[218:219], off
	s_waitcnt vmcnt(8)
	s_waitcnt lgkmcnt(0)
	s_barrier
	s_setprio 1
	s_waitcnt lgkmcnt(0)
	v_mfma_f32_16x16x32_bf16 v[126:129], v[142:145], v[178:181], v[126:129]
	v_mfma_f32_16x16x32_bf16 v[126:129], v[146:149], v[182:185], v[126:129]
	v_mfma_f32_16x16x32_bf16 v[110:113], v[142:145], v[186:189], v[110:113]
	v_mfma_f32_16x16x32_bf16 v[110:113], v[146:149], v[190:193], v[110:113]
	v_mfma_f32_16x16x32_bf16 v[94:97], v[142:145], v[194:197], v[94:97]
	v_mfma_f32_16x16x32_bf16 v[94:97], v[146:149], v[198:201], v[94:97]
	v_mfma_f32_16x16x32_bf16 v[78:81], v[142:145], v[202:205], v[78:81]
	v_mfma_f32_16x16x32_bf16 v[78:81], v[146:149], v[206:209], v[78:81]
	v_mfma_f32_16x16x32_bf16 v[74:77], v[150:153], v[202:205], v[74:77]
	v_mfma_f32_16x16x32_bf16 v[74:77], v[154:157], v[206:209], v[74:77]
	v_mfma_f32_16x16x32_bf16 v[90:93], v[150:153], v[194:197], v[90:93]
	v_mfma_f32_16x16x32_bf16 v[90:93], v[154:157], v[198:201], v[90:93]
	v_mfma_f32_16x16x32_bf16 v[106:109], v[150:153], v[186:189], v[106:109]
	v_mfma_f32_16x16x32_bf16 v[106:109], v[154:157], v[190:193], v[106:109]
	v_mfma_f32_16x16x32_bf16 v[122:125], v[150:153], v[178:181], v[122:125]
	v_mfma_f32_16x16x32_bf16 v[122:125], v[154:157], v[182:185], v[122:125]
	s_setprio 0
	s_setprio 1
	v_mfma_f32_16x16x32_bf16 v[118:121], v[162:165], v[178:181], v[118:121]
	v_mfma_f32_16x16x32_bf16 v[118:121], v[166:169], v[182:185], v[118:121]
	v_mfma_f32_16x16x32_bf16 v[102:105], v[162:165], v[186:189], v[102:105]
	v_mfma_f32_16x16x32_bf16 v[102:105], v[166:169], v[190:193], v[102:105]
	v_mfma_f32_16x16x32_bf16 v[86:89], v[162:165], v[194:197], v[86:89]
	v_mfma_f32_16x16x32_bf16 v[86:89], v[166:169], v[198:201], v[86:89]
	v_mfma_f32_16x16x32_bf16 v[70:73], v[162:165], v[202:205], v[70:73]
	v_mfma_f32_16x16x32_bf16 v[70:73], v[166:169], v[206:209], v[70:73]
	v_mfma_f32_16x16x32_bf16 v[66:69], v[170:173], v[202:205], v[66:69]
	v_mfma_f32_16x16x32_bf16 v[66:69], v[174:177], v[206:209], v[66:69]
	v_mfma_f32_16x16x32_bf16 v[82:85], v[170:173], v[194:197], v[82:85]
	v_mfma_f32_16x16x32_bf16 v[82:85], v[174:177], v[198:201], v[82:85]
	v_mfma_f32_16x16x32_bf16 v[98:101], v[170:173], v[186:189], v[98:101]
	v_mfma_f32_16x16x32_bf16 v[98:101], v[174:177], v[190:193], v[98:101]
	v_mfma_f32_16x16x32_bf16 v[114:117], v[170:173], v[178:181], v[114:117]
	v_mfma_f32_16x16x32_bf16 v[114:117], v[174:177], v[182:185], v[114:117]
	s_setprio 0
	s_barrier
; #define PG8_STAGE(bufoff, gbase, voff) do { _Pragma("unroll") for (int _i = 0; _i < 2; ++_i) \
;         __builtin_amdgcn_global_load_lds((const unsigned*)((const char*)(gbase) + (voff)[_i]), (LAS unsigned*)(lds + (bufoff) + ldsw + _i * 8192), 16, 0, 0); } while (0)
; #define PG8_LDA(dst, b, h) do { _Pragma("unroll") for (int m = 0; m < 4; ++m) _Pragma("unroll") for (int k = 0; k < 2; ++k) dst[m][k] = *(const LAS bf16x8*)(lds + PG8_SA(b, h) + aoff + m * 2048 + k * 1024); } while (0)
; #define PG8_MMA(ai, bj, At, Bt) do { __builtin_amdgcn_s_setprio(1); _Pragma("unroll") for (int m = 0; m < 4; ++m) _Pragma("unroll") for (int n = 0; n < 2; ++n) _Pragma("unroll") for (int k = 0; k < 2; ++k) \
;         acc[ai][bj][m][n] = __builtin_amdgcn_mfma_f32_16x16x32_bf16(Bt[n][k], At[m][k], acc[ai][bj][m][n], 0, 0, 0); __builtin_amdgcn_s_setprio(0); } while (0)
; #define PG8_WAIT_V(n) asm volatile("s_waitcnt vmcnt(" #n ")" ::: "memory")
; #define PG8_WAIT_L(n) asm volatile("s_waitcnt lgkmcnt(" #n ")" ::: "memory")
; #define PG8_BAR __builtin_amdgcn_s_barrier()
; #define PG8_SCHED __builtin_amdgcn_sched_barrier(0)
; template <class Epi, class Sched, bool ALIGN_EPI = false, bool SP2 = false>
; __device__ __forceinline__ void gemm_phase(LAS unsigned char* lds, const Gemm g, const Sched& S, const Epi& E) {
;     ...
;         for (int t = 0; t < nt; t += 2) {
;             const bool last = (t == nt - 2);
;             const char* a1 = cA + (size_t)(t + 1) * kstep;
;             const char* a2 = last ? nA : cA + (size_t)(t + 2) * kstep; const char* b2 = last ? nB : cB + (size_t)(t + 2) * kstep;
;     ...
;             PG8_LDA(At, 1, 1); PG8_STAGE(PG8_SB(1, 0), b3, voffB); PG8_STAGE(PG8_SB(1, 1), b3 + hstep, voffB); PG8_STAGE(PG8_SA(1, 0), a3, voffA);
;             PG8_WAIT_V(8); PG8_WAIT_L(0); PG8_BAR; PG8_MMA(1, 0, At, B0); PG8_MMA(1, 1, At, B1); PG8_BAR; PG8_SCHED;
	s_add_i32 s30, s41, s9
	v_lshl_add_u64 v[210:211], v[210:211], 0, s[12:13]
	s_mov_b32 m0, s30
	ds_read_b128 v[178:181], v161 offset:49152
	ds_read_b128 v[182:185], v161 offset:50176
	ds_read_b128 v[186:189], v161 offset:51200
	ds_read_b128 v[190:193], v161 offset:52224
	ds_read_b128 v[194:197], v161 offset:53248
	ds_read_b128 v[198:201], v161 offset:54272
	ds_read_b128 v[202:205], v161 offset:55296
	ds_read_b128 v[206:209], v161 offset:56320
	global_load_lds_dwordx4 v[210:211], off
	s_add_i32 m0, s30, 0x2000
	s_add_u32 s28, s28, 0x80080
	v_lshl_add_u64 v[210:211], v[212:213], 0, s[12:13]
	s_addc_u32 s29, s29, 0
	s_add_i32 s30, s57, s9
	global_load_lds_dwordx4 v[210:211], off
	v_lshl_add_u64 v[210:211], s[28:29], 0, v[134:135]
	s_mov_b32 m0, s30
	s_nop 0
	global_load_lds_dwordx4 v[210:211], off
	v_lshl_add_u64 v[210:211], s[28:29], 0, v[130:131]
	s_add_i32 m0, s30, 0x2000
	s_nop 0
	global_load_lds_dwordx4 v[210:211], off
	v_lshl_add_u64 v[210:211], v[214:215], 0, s[12:13]
	s_mov_b32 m0, s53
	s_nop 0
	global_load_lds_dwordx4 v[210:211], off
	v_lshl_add_u64 v[210:211], v[216:217], 0, s[12:13]
	s_mov_b32 m0, s54
	s_nop 0
	global_load_lds_dwordx4 v[210:211], off
	s_waitcnt vmcnt(8)
	s_waitcnt lgkmcnt(0)
	s_barrier
	s_setprio 1
	s_waitcnt lgkmcnt(0)
	v_mfma_f32_16x16x32_bf16 v[62:65], v[142:145], v[178:181], v[62:65]
	v_mfma_f32_16x16x32_bf16 v[62:65], v[146:149], v[182:185], v[62:65]
	v_mfma_f32_16x16x32_bf16 v[46:49], v[142:145], v[186:189], v[46:49]
	v_mfma_f32_16x16x32_bf16 v[46:49], v[146:149], v[190:193], v[46:49]
	v_mfma_f32_16x16x32_bf16 v[30:33], v[142:145], v[194:197], v[30:33]
	v_mfma_f32_16x16x32_bf16 v[30:33], v[146:149], v[198:201], v[30:33]
	v_mfma_f32_16x16x32_bf16 v[14:17], v[142:145], v[202:205], v[14:17]
	v_mfma_f32_16x16x32_bf16 v[14:17], v[146:149], v[206:209], v[14:17]
	v_mfma_f32_16x16x32_bf16 v[10:13], v[150:153], v[202:205], v[10:13]
	v_mfma_f32_16x16x32_bf16 v[10:13], v[154:157], v[206:209], v[10:13]
	v_mfma_f32_16x16x32_bf16 v[26:29], v[150:153], v[194:197], v[26:29]
	v_mfma_f32_16x16x32_bf16 v[26:29], v[154:157], v[198:201], v[26:29]
	v_mfma_f32_16x16x32_bf16 v[42:45], v[150:153], v[186:189], v[42:45]
	v_mfma_f32_16x16x32_bf16 v[42:45], v[154:157], v[190:193], v[42:45]
	v_mfma_f32_16x16x32_bf16 v[58:61], v[150:153], v[178:181], v[58:61]
	v_mfma_f32_16x16x32_bf16 v[58:61], v[154:157], v[182:185], v[58:61]
	s_setprio 0
	s_setprio 1
	v_mfma_f32_16x16x32_bf16 v[54:57], v[162:165], v[178:181], v[54:57]
	v_mfma_f32_16x16x32_bf16 v[54:57], v[166:169], v[182:185], v[54:57]
	v_mfma_f32_16x16x32_bf16 v[38:41], v[162:165], v[186:189], v[38:41]
	v_mfma_f32_16x16x32_bf16 v[38:41], v[166:169], v[190:193], v[38:41]
	v_mfma_f32_16x16x32_bf16 v[22:25], v[162:165], v[194:197], v[22:25]
	v_mfma_f32_16x16x32_bf16 v[22:25], v[166:169], v[198:201], v[22:25]
	v_mfma_f32_16x16x32_bf16 v[6:9], v[162:165], v[202:205], v[6:9]
	v_mfma_f32_16x16x32_bf16 v[6:9], v[166:169], v[206:209], v[6:9]
	v_mfma_f32_16x16x32_bf16 v[2:5], v[170:173], v[202:205], v[2:5]
	v_mfma_f32_16x16x32_bf16 v[2:5], v[174:177], v[206:209], v[2:5]
	v_mfma_f32_16x16x32_bf16 v[18:21], v[170:173], v[194:197], v[18:21]
	v_mfma_f32_16x16x32_bf16 v[18:21], v[174:177], v[198:201], v[18:21]
	v_mfma_f32_16x16x32_bf16 v[34:37], v[170:173], v[186:189], v[34:37]
	v_mfma_f32_16x16x32_bf16 v[34:37], v[174:177], v[190:193], v[34:37]
	v_mfma_f32_16x16x32_bf16 v[50:53], v[170:173], v[178:181], v[50:53]
	v_mfma_f32_16x16x32_bf16 v[50:53], v[174:177], v[182:185], v[50:53]
	s_setprio 0
	s_barrier
	s_add_i32 s40, s40, 2
	s_add_u32 s26, s26, 0x100
	s_addc_u32 s27, s27, 0
	s_add_u32 s21, s21, 0x100
	s_addc_u32 s35, s35, 0
	s_cmp_gt_u32 s40, 29
	s_cbranch_scc0 .LBB0_359
	s_and_b64 vcc, exec, s[16:17]
	s_cbranch_vccz .LBB0_362
	s_barrier

; #define PG8_STAGE(bufoff, gbase, voff) do { _Pragma("unroll") for (int _i = 0; _i < 2; ++_i) \
;         __builtin_amdgcn_global_load_lds((const unsigned*)((const char*)(gbase) + (voff)[_i]), (LAS unsigned*)(lds + (bufoff) + ldsw + _i * 8192), 16, 0, 0); } while (0)
; #define PG8_LDA(dst, b, h) do { _Pragma("unroll") for (int m = 0; m < 4; ++m) _Pragma("unroll") for (int k = 0; k < 2; ++k) dst[m][k] = *(const LAS bf16x8*)(lds + PG8_SA(b, h) + aoff + m * 2048 + k * 1024); } while (0)
; #define PG8_LDB(dst, b, h) do { _Pragma("unroll") for (int n = 0; n < 2; ++n) _Pragma("unroll") for (int k = 0; k < 2; ++k) dst[n][k] = *(const LAS bf16x8*)(lds + PG8_SB(b, h) + boff + n * 2048 + k * 1024); } while (0)
; #define PG8_MMA(ai, bj, At, Bt) do { __builtin_amdgcn_s_setprio(1); _Pragma("unroll") for (int m = 0; m < 4; ++m) _Pragma("unroll") for (int n = 0; n < 2; ++n) _Pragma("unroll") for (int k = 0; k < 2; ++k) \
;         acc[ai][bj][m][n] = __builtin_amdgcn_mfma_f32_16x16x32_bf16(Bt[n][k], At[m][k], acc[ai][bj][m][n], 0, 0, 0); __builtin_amdgcn_s_setprio(0); } while (0)
; #define PG8_WAIT_V(n) asm volatile("s_waitcnt vmcnt(" #n ")" ::: "memory")
; #define PG8_WAIT_L(n) asm volatile("s_waitcnt lgkmcnt(" #n ")" ::: "memory")
; #define PG8_BAR __builtin_amdgcn_s_barrier()
; #define PG8_SCHED __builtin_amdgcn_sched_barrier(0)
; template <class Epi, class Sched, bool ALIGN_EPI = false, bool SP2 = false>
; __device__ __forceinline__ void gemm_phase(LAS unsigned char* lds, const Gemm g, const Sched& S, const Epi& E) {
;     ...
;             PG8_LDB(B0, 0, 0); PG8_LDB(B1, 0, 1); PG8_SCHED; PG8_LDA(At, 0, 0); PG8_STAGE(PG8_SA(1, 1), a1 + hstep, voffA);
;             PG8_WAIT_V(8); PG8_WAIT_L(0); PG8_BAR; PG8_MMA(0, 0, At, B0); PG8_MMA(0, 1, At, B1); PG8_BAR; PG8_SCHED;
;             PG8_LDA(At, 0, 1); PG8_STAGE(PG8_SB(0, 0), b2, voffB); PG8_STAGE(PG8_SB(0, 1), b2 + hstep, voffB); PG8_STAGE(PG8_SA(0, 0), a2, voffA);
;             PG8_WAIT_V(8); PG8_WAIT_L(0); PG8_BAR; PG8_MMA(1, 0, At, B0); PG8_MMA(1, 1, At, B1); PG8_BAR; PG8_SCHED;
.LBB0_833:
	s_add_u32 s28, s26, 0xfff80080
	s_addc_u32 s29, s27, -1
	s_add_i32 s53, 0, 0x10000
	s_cmp_eq_u32 s52, 28
	s_cselect_b32 s31, s21, s29
	s_cselect_b32 s30, s48, s28
	s_cselect_b32 s29, s19, s51
	s_cselect_b32 s28, s49, s50
	s_add_i32 s56, 0, 0x14000
	v_add_u32_e32 v134, s53, v247
	v_add_u32_e32 v158, s56, v247
	ds_read_b128 v[106:109], v134
	ds_read_b128 v[110:113], v134 offset:1024
	ds_read_b128 v[122:125], v134 offset:2048
	ds_read_b128 v[134:137], v134 offset:3072
	ds_read_b128 v[146:149], v158
	ds_read_b128 v[150:153], v158 offset:1024
	ds_read_b128 v[154:157], v158 offset:2048
	ds_read_b128 v[158:161], v158 offset:3072
	v_lshl_add_u64 v[204:205], s[26:27], 0, v[200:201]
	s_add_i32 m0, s8, 0xc000
	ds_read_b128 v[162:165], v249
	ds_read_b128 v[166:169], v249 offset:1024
	ds_read_b128 v[170:173], v249 offset:2048
	ds_read_b128 v[174:177], v249 offset:3072
	ds_read_b128 v[178:181], v249 offset:4096
	ds_read_b128 v[182:185], v249 offset:5120
	ds_read_b128 v[186:189], v249 offset:6144
	ds_read_b128 v[190:193], v249 offset:7168
	global_load_lds_dwordx4 v[204:205], off
	v_lshl_add_u64 v[204:205], s[26:27], 0, v[202:203]
	s_add_i32 m0, s8, 0xe000
	s_nop 0
	global_load_lds_dwordx4 v[204:205], off
	s_waitcnt vmcnt(8)
	s_waitcnt lgkmcnt(0)
	s_barrier
	s_setprio 1
	s_waitcnt lgkmcnt(0)
	v_mfma_f32_16x16x32_bf16 v[142:145], v[106:109], v[162:165], v[142:145]
	v_mfma_f32_16x16x32_bf16 v[142:145], v[110:113], v[166:169], v[142:145]
	v_mfma_f32_16x16x32_bf16 v[118:121], v[106:109], v[170:173], v[118:121]
	v_mfma_f32_16x16x32_bf16 v[118:121], v[110:113], v[174:177], v[118:121]
	v_mfma_f32_16x16x32_bf16 v[94:97], v[106:109], v[178:181], v[94:97]
	v_mfma_f32_16x16x32_bf16 v[94:97], v[110:113], v[182:185], v[94:97]
	v_mfma_f32_16x16x32_bf16 v[78:81], v[106:109], v[186:189], v[78:81]
	v_mfma_f32_16x16x32_bf16 v[78:81], v[110:113], v[190:193], v[78:81]
	v_mfma_f32_16x16x32_bf16 v[74:77], v[122:125], v[186:189], v[74:77]
	v_mfma_f32_16x16x32_bf16 v[74:77], v[134:137], v[190:193], v[74:77]
	v_mfma_f32_16x16x32_bf16 v[90:93], v[122:125], v[178:181], v[90:93]
	v_mfma_f32_16x16x32_bf16 v[90:93], v[134:137], v[182:185], v[90:93]
	v_mfma_f32_16x16x32_bf16 v[114:117], v[122:125], v[170:173], v[114:117]
	v_mfma_f32_16x16x32_bf16 v[114:117], v[134:137], v[174:177], v[114:117]
	v_mfma_f32_16x16x32_bf16 v[138:141], v[122:125], v[162:165], v[138:141]
	v_mfma_f32_16x16x32_bf16 v[138:141], v[134:137], v[166:169], v[138:141]
	s_setprio 0
	s_setprio 1
	v_mfma_f32_16x16x32_bf16 v[130:133], v[146:149], v[162:165], v[130:133]
	v_mfma_f32_16x16x32_bf16 v[130:133], v[150:153], v[166:169], v[130:133]
	v_mfma_f32_16x16x32_bf16 v[102:105], v[146:149], v[170:173], v[102:105]
	v_mfma_f32_16x16x32_bf16 v[102:105], v[150:153], v[174:177], v[102:105]
	v_mfma_f32_16x16x32_bf16 v[86:89], v[146:149], v[178:181], v[86:89]
	v_mfma_f32_16x16x32_bf16 v[86:89], v[150:153], v[182:185], v[86:89]
	v_mfma_f32_16x16x32_bf16 v[70:73], v[146:149], v[186:189], v[70:73]
	v_mfma_f32_16x16x32_bf16 v[70:73], v[150:153], v[190:193], v[70:73]
	v_mfma_f32_16x16x32_bf16 v[66:69], v[154:157], v[186:189], v[66:69]
	v_mfma_f32_16x16x32_bf16 v[66:69], v[158:161], v[190:193], v[66:69]
	v_mfma_f32_16x16x32_bf16 v[82:85], v[154:157], v[178:181], v[82:85]
	v_mfma_f32_16x16x32_bf16 v[82:85], v[158:161], v[182:185], v[82:85]
	v_mfma_f32_16x16x32_bf16 v[98:101], v[154:157], v[170:173], v[98:101]
	v_mfma_f32_16x16x32_bf16 v[98:101], v[158:161], v[174:177], v[98:101]
	v_mfma_f32_16x16x32_bf16 v[126:129], v[154:157], v[162:165], v[126:129]
	v_mfma_f32_16x16x32_bf16 v[126:129], v[158:161], v[166:169], v[126:129]
	s_setprio 0
	s_barrier
	s_add_i32 s53, s53, s7
	v_lshl_add_u64 v[204:205], s[28:29], 0, v[0:1]
	s_mov_b32 m0, s53
	ds_read_b128 v[162:165], v249 offset:16384
	ds_read_b128 v[166:169], v249 offset:17408
	ds_read_b128 v[170:173], v249 offset:18432
	ds_read_b128 v[174:177], v249 offset:19456
	ds_read_b128 v[178:181], v249 offset:20480
	ds_read_b128 v[182:185], v249 offset:21504
	ds_read_b128 v[186:189], v249 offset:22528
	ds_read_b128 v[190:193], v249 offset:23552
	global_load_lds_dwordx4 v[204:205], off
	s_add_i32 m0, s53, 0x2000
	s_add_u32 s54, s28, 0x80000
	v_lshl_add_u64 v[206:207], s[28:29], 0, v[194:195]
	s_addc_u32 s55, s29, 0
	s_add_i32 s53, s56, s7
	global_load_lds_dwordx4 v[206:207], off
	v_lshl_add_u64 v[208:209], s[54:55], 0, v[0:1]
	s_mov_b32 m0, s53
	v_lshl_add_u64 v[210:211], s[30:31], 0, v[196:197]
	global_load_lds_dwordx4 v[208:209], off
	v_lshl_add_u64 v[208:209], s[54:55], 0, v[194:195]
	s_add_i32 m0, s53, 0x2000
	s_nop 0
	global_load_lds_dwordx4 v[208:209], off
	v_lshl_add_u64 v[208:209], s[30:31], 0, v[198:199]
	s_mov_b32 m0, s8
	s_nop 0
	global_load_lds_dwordx4 v[208:209], off
	s_mov_b32 m0, s9
	s_nop 0
	global_load_lds_dwordx4 v[210:211], off
	s_waitcnt vmcnt(8)
	s_waitcnt lgkmcnt(0)
	s_barrier
; #define PG8_STAGE(bufoff, gbase, voff) do { _Pragma("unroll") for (int _i = 0; _i < 2; ++_i) \
;         __builtin_amdgcn_global_load_lds((const unsigned*)((const char*)(gbase) + (voff)[_i]), (LAS unsigned*)(lds + (bufoff) + ldsw + _i * 8192), 16, 0, 0); } while (0)
; #define PG8_LDA(dst, b, h) do { _Pragma("unroll") for (int m = 0; m < 4; ++m) _Pragma("unroll") for (int k = 0; k < 2; ++k) dst[m][k] = *(const LAS bf16x8*)(lds + PG8_SA(b, h) + aoff + m * 2048 + k * 1024); } while (0)
; #define PG8_LDB(dst, b, h) do { _Pragma("unroll") for (int n = 0; n < 2; ++n) _Pragma("unroll") for (int k = 0; k < 2; ++k) dst[n][k] = *(const LAS bf16x8*)(lds + PG8_SB(b, h) + boff + n * 2048 + k * 1024); } while (0)
; #define PG8_MMA(ai, bj, At, Bt) do { __builtin_amdgcn_s_setprio(1); _Pragma("unroll") for (int m = 0; m < 4; ++m) _Pragma("unroll") for (int n = 0; n < 2; ++n) _Pragma("unroll") for (int k = 0; k < 2; ++k) \
;         acc[ai][bj][m][n] = __builtin_amdgcn_mfma_f32_16x16x32_bf16(Bt[n][k], At[m][k], acc[ai][bj][m][n], 0, 0, 0); __builtin_amdgcn_s_setprio(0); } while (0)
; #define PG8_WAIT_V(n) asm volatile("s_waitcnt vmcnt(" #n ")" ::: "memory")
; #define PG8_WAIT_L(n) asm volatile("s_waitcnt lgkmcnt(" #n ")" ::: "memory")
; #define PG8_BAR __builtin_amdgcn_s_barrier()
; #define PG8_SCHED __builtin_amdgcn_sched_barrier(0)
; template <class Epi, class Sched, bool ALIGN_EPI = false, bool SP2 = false>
; __device__ __forceinline__ void gemm_phase(LAS unsigned char* lds, const Gemm g, const Sched& S, const Epi& E) {
;     ...
;             PG8_WAIT_V(8); PG8_WAIT_L(0); PG8_BAR; PG8_MMA(1, 0, At, B0); PG8_MMA(1, 1, At, B1); PG8_BAR; PG8_SCHED;
;             PG8_LDB(B0, 1, 0); PG8_LDB(B1, 1, 1); PG8_SCHED; PG8_LDA(At, 1, 0); PG8_STAGE(PG8_SA(0, 1), a2 + hstep, voffA);
;             PG8_WAIT_V(8); PG8_WAIT_L(0); PG8_BAR; PG8_MMA(0, 0, At, B0); PG8_MMA(0, 1, At, B1); PG8_BAR; PG8_SCHED;
	s_setprio 1
	s_waitcnt lgkmcnt(0)
	v_mfma_f32_16x16x32_bf16 v[62:65], v[106:109], v[162:165], v[62:65]
	v_mfma_f32_16x16x32_bf16 v[62:65], v[110:113], v[166:169], v[62:65]
	v_mfma_f32_16x16x32_bf16 v[46:49], v[106:109], v[170:173], v[46:49]
	v_mfma_f32_16x16x32_bf16 v[46:49], v[110:113], v[174:177], v[46:49]
	v_mfma_f32_16x16x32_bf16 v[30:33], v[106:109], v[178:181], v[30:33]
	v_mfma_f32_16x16x32_bf16 v[30:33], v[110:113], v[182:185], v[30:33]
	v_mfma_f32_16x16x32_bf16 v[14:17], v[106:109], v[186:189], v[14:17]
	v_mfma_f32_16x16x32_bf16 v[14:17], v[110:113], v[190:193], v[14:17]
	v_mfma_f32_16x16x32_bf16 v[10:13], v[122:125], v[186:189], v[10:13]
	v_mfma_f32_16x16x32_bf16 v[10:13], v[134:137], v[190:193], v[10:13]
	v_mfma_f32_16x16x32_bf16 v[26:29], v[122:125], v[178:181], v[26:29]
	v_mfma_f32_16x16x32_bf16 v[26:29], v[134:137], v[182:185], v[26:29]
	v_mfma_f32_16x16x32_bf16 v[42:45], v[122:125], v[170:173], v[42:45]
	v_mfma_f32_16x16x32_bf16 v[42:45], v[134:137], v[174:177], v[42:45]
	v_mfma_f32_16x16x32_bf16 v[58:61], v[122:125], v[162:165], v[58:61]
	v_mfma_f32_16x16x32_bf16 v[58:61], v[134:137], v[166:169], v[58:61]
	s_setprio 0
	s_setprio 1
	v_mfma_f32_16x16x32_bf16 v[54:57], v[146:149], v[162:165], v[54:57]
	v_mfma_f32_16x16x32_bf16 v[54:57], v[150:153], v[166:169], v[54:57]
	v_mfma_f32_16x16x32_bf16 v[38:41], v[146:149], v[170:173], v[38:41]
	v_mfma_f32_16x16x32_bf16 v[38:41], v[150:153], v[174:177], v[38:41]
	v_mfma_f32_16x16x32_bf16 v[22:25], v[146:149], v[178:181], v[22:25]
	v_mfma_f32_16x16x32_bf16 v[22:25], v[150:153], v[182:185], v[22:25]
	v_mfma_f32_16x16x32_bf16 v[6:9], v[146:149], v[186:189], v[6:9]
	v_mfma_f32_16x16x32_bf16 v[6:9], v[150:153], v[190:193], v[6:9]
	v_mfma_f32_16x16x32_bf16 v[2:5], v[154:157], v[186:189], v[2:5]
	v_mfma_f32_16x16x32_bf16 v[2:5], v[158:161], v[190:193], v[2:5]
	v_mfma_f32_16x16x32_bf16 v[18:21], v[154:157], v[178:181], v[18:21]
	v_mfma_f32_16x16x32_bf16 v[18:21], v[158:161], v[182:185], v[18:21]
	v_mfma_f32_16x16x32_bf16 v[34:37], v[154:157], v[170:173], v[34:37]
	v_mfma_f32_16x16x32_bf16 v[34:37], v[158:161], v[174:177], v[34:37]
	v_mfma_f32_16x16x32_bf16 v[50:53], v[154:157], v[162:165], v[50:53]
	v_mfma_f32_16x16x32_bf16 v[50:53], v[158:161], v[166:169], v[50:53]
	s_setprio 0
	s_barrier
	s_add_i32 s53, 0, 0x18000
	s_add_i32 s54, 0, 0x1c000
	v_add_u32_e32 v134, s53, v247
	v_add_u32_e32 v158, s54, v247
	ds_read_b128 v[106:109], v134
	ds_read_b128 v[110:113], v134 offset:1024
	ds_read_b128 v[122:125], v134 offset:2048
	ds_read_b128 v[134:137], v134 offset:3072
	ds_read_b128 v[146:149], v158
	ds_read_b128 v[150:153], v158 offset:1024
	ds_read_b128 v[154:157], v158 offset:2048
	ds_read_b128 v[158:161], v158 offset:3072
	s_add_u32 s30, s30, 0x80000
	s_addc_u32 s31, s31, 0
	s_mov_b32 m0, s35
	v_lshl_add_u64 v[212:213], s[30:31], 0, v[198:199]
	ds_read_b128 v[162:165], v249 offset:32768
	ds_read_b128 v[166:169], v249 offset:33792
	ds_read_b128 v[170:173], v249 offset:34816
	ds_read_b128 v[174:177], v249 offset:35840
	ds_read_b128 v[178:181], v249 offset:36864
	ds_read_b128 v[182:185], v249 offset:37888
	ds_read_b128 v[186:189], v249 offset:38912
	ds_read_b128 v[190:193], v249 offset:39936
	global_load_lds_dwordx4 v[212:213], off
	v_lshl_add_u64 v[212:213], s[30:31], 0, v[196:197]
	s_mov_b32 m0, s42
	s_nop 0
	global_load_lds_dwordx4 v[212:213], off
	s_waitcnt vmcnt(8)
	s_waitcnt lgkmcnt(0)
	s_barrier
	s_setprio 1
	s_waitcnt lgkmcnt(0)
	v_mfma_f32_16x16x32_bf16 v[142:145], v[106:109], v[162:165], v[142:145]
	v_mfma_f32_16x16x32_bf16 v[142:145], v[110:113], v[166:169], v[142:145]
	v_mfma_f32_16x16x32_bf16 v[118:121], v[106:109], v[170:173], v[118:121]
	v_mfma_f32_16x16x32_bf16 v[118:121], v[110:113], v[174:177], v[118:121]
	v_mfma_f32_16x16x32_bf16 v[94:97], v[106:109], v[178:181], v[94:97]
	v_mfma_f32_16x16x32_bf16 v[94:97], v[110:113], v[182:185], v[94:97]
	v_mfma_f32_16x16x32_bf16 v[78:81], v[106:109], v[186:189], v[78:81]
	v_mfma_f32_16x16x32_bf16 v[78:81], v[110:113], v[190:193], v[78:81]
	v_mfma_f32_16x16x32_bf16 v[74:77], v[122:125], v[186:189], v[74:77]
	v_mfma_f32_16x16x32_bf16 v[74:77], v[134:137], v[190:193], v[74:77]
	v_mfma_f32_16x16x32_bf16 v[90:93], v[122:125], v[178:181], v[90:93]
	v_mfma_f32_16x16x32_bf16 v[90:93], v[134:137], v[182:185], v[90:93]
	v_mfma_f32_16x16x32_bf16 v[114:117], v[122:125], v[170:173], v[114:117]
	v_mfma_f32_16x16x32_bf16 v[114:117], v[134:137], v[174:177], v[114:117]
	v_mfma_f32_16x16x32_bf16 v[138:141], v[122:125], v[162:165], v[138:141]
	v_mfma_f32_16x16x32_bf16 v[138:141], v[134:137], v[166:169], v[138:141]
	s_setprio 0
	s_setprio 1
	v_mfma_f32_16x16x32_bf16 v[130:133], v[146:149], v[162:165], v[130:133]
	v_mfma_f32_16x16x32_bf16 v[130:133], v[150:153], v[166:169], v[130:133]
	v_mfma_f32_16x16x32_bf16 v[102:105], v[146:149], v[170:173], v[102:105]
	v_mfma_f32_16x16x32_bf16 v[102:105], v[150:153], v[174:177], v[102:105]
	v_mfma_f32_16x16x32_bf16 v[86:89], v[146:149], v[178:181], v[86:89]
	v_mfma_f32_16x16x32_bf16 v[86:89], v[150:153], v[182:185], v[86:89]
	v_mfma_f32_16x16x32_bf16 v[70:73], v[146:149], v[186:189], v[70:73]
	v_mfma_f32_16x16x32_bf16 v[70:73], v[150:153], v[190:193], v[70:73]
	v_mfma_f32_16x16x32_bf16 v[66:69], v[154:157], v[186:189], v[66:69]
	v_mfma_f32_16x16x32_bf16 v[66:69], v[158:161], v[190:193], v[66:69]
	v_mfma_f32_16x16x32_bf16 v[82:85], v[154:157], v[178:181], v[82:85]
	v_mfma_f32_16x16x32_bf16 v[82:85], v[158:161], v[182:185], v[82:85]
	v_mfma_f32_16x16x32_bf16 v[98:101], v[154:157], v[170:173], v[98:101]
	v_mfma_f32_16x16x32_bf16 v[98:101], v[158:161], v[174:177], v[98:101]
	v_mfma_f32_16x16x32_bf16 v[126:129], v[154:157], v[162:165], v[126:129]
	v_mfma_f32_16x16x32_bf16 v[126:129], v[158:161], v[166:169], v[126:129]
	s_setprio 0
	s_barrier
; #define PG8_STAGE(bufoff, gbase, voff) do { _Pragma("unroll") for (int _i = 0; _i < 2; ++_i) \
;         __builtin_amdgcn_global_load_lds((const unsigned*)((const char*)(gbase) + (voff)[_i]), (LAS unsigned*)(lds + (bufoff) + ldsw + _i * 8192), 16, 0, 0); } while (0)
; #define PG8_LDA(dst, b, h) do { _Pragma("unroll") for (int m = 0; m < 4; ++m) _Pragma("unroll") for (int k = 0; k < 2; ++k) dst[m][k] = *(const LAS bf16x8*)(lds + PG8_SA(b, h) + aoff + m * 2048 + k * 1024); } while (0)
; #define PG8_MMA(ai, bj, At, Bt) do { __builtin_amdgcn_s_setprio(1); _Pragma("unroll") for (int m = 0; m < 4; ++m) _Pragma("unroll") for (int n = 0; n < 2; ++n) _Pragma("unroll") for (int k = 0; k < 2; ++k) \
;         acc[ai][bj][m][n] = __builtin_amdgcn_mfma_f32_16x16x32_bf16(Bt[n][k], At[m][k], acc[ai][bj][m][n], 0, 0, 0); __builtin_amdgcn_s_setprio(0); } while (0)
; #define PG8_WAIT_V(n) asm volatile("s_waitcnt vmcnt(" #n ")" ::: "memory")
; #define PG8_WAIT_L(n) asm volatile("s_waitcnt lgkmcnt(" #n ")" ::: "memory")
; #define PG8_BAR __builtin_amdgcn_s_barrier()
; #define PG8_SCHED __builtin_amdgcn_sched_barrier(0)
; template <class Epi, class Sched, bool ALIGN_EPI = false, bool SP2 = false>
; __device__ __forceinline__ void gemm_phase(LAS unsigned char* lds, const Gemm g, const Sched& S, const Epi& E) {
;     ...
;         for (int t = 0; t < nt; t += 2) {
;             const bool last = (t == nt - 2);
;             const char* a1 = cA + (size_t)(t + 1) * kstep;
;             const char* a2 = last ? nA : cA + (size_t)(t + 2) * kstep; const char* b2 = last ? nB : cB + (size_t)(t + 2) * kstep;
;     ...
;             PG8_LDA(At, 1, 1); PG8_STAGE(PG8_SB(1, 0), b3, voffB); PG8_STAGE(PG8_SB(1, 1), b3 + hstep, voffB); PG8_STAGE(PG8_SA(1, 0), a3, voffA);
;             PG8_WAIT_V(8); PG8_WAIT_L(0); PG8_BAR; PG8_MMA(1, 0, At, B0); PG8_MMA(1, 1, At, B1); PG8_BAR; PG8_SCHED;
	s_add_i32 s30, s53, s7
	v_lshl_add_u64 v[204:205], v[204:205], 0, s[12:13]
	s_mov_b32 m0, s30
	ds_read_b128 v[162:165], v249 offset:49152
	ds_read_b128 v[166:169], v249 offset:50176
	ds_read_b128 v[170:173], v249 offset:51200
	ds_read_b128 v[174:177], v249 offset:52224
	ds_read_b128 v[178:181], v249 offset:53248
	ds_read_b128 v[182:185], v249 offset:54272
	ds_read_b128 v[186:189], v249 offset:55296
	ds_read_b128 v[190:193], v249 offset:56320
	global_load_lds_dwordx4 v[204:205], off
	s_add_i32 m0, s30, 0x2000
	s_add_u32 s28, s28, 0x80080
	v_lshl_add_u64 v[204:205], v[206:207], 0, s[12:13]
	s_addc_u32 s29, s29, 0
	s_add_i32 s30, s54, s7
	global_load_lds_dwordx4 v[204:205], off
	v_lshl_add_u64 v[204:205], s[28:29], 0, v[0:1]
	s_mov_b32 m0, s30
	s_nop 0
	global_load_lds_dwordx4 v[204:205], off
	v_lshl_add_u64 v[204:205], s[28:29], 0, v[194:195]
	s_add_i32 m0, s30, 0x2000
	s_nop 0
	global_load_lds_dwordx4 v[204:205], off
	v_lshl_add_u64 v[204:205], v[208:209], 0, s[12:13]
	s_mov_b32 m0, s43
	s_nop 0
	global_load_lds_dwordx4 v[204:205], off
	v_lshl_add_u64 v[204:205], v[210:211], 0, s[12:13]
	s_mov_b32 m0, s44
	s_nop 0
	global_load_lds_dwordx4 v[204:205], off
	s_waitcnt vmcnt(8)
	s_waitcnt lgkmcnt(0)
	s_barrier
	s_setprio 1
	s_waitcnt lgkmcnt(0)
	v_mfma_f32_16x16x32_bf16 v[62:65], v[106:109], v[162:165], v[62:65]
	v_mfma_f32_16x16x32_bf16 v[62:65], v[110:113], v[166:169], v[62:65]
	v_mfma_f32_16x16x32_bf16 v[46:49], v[106:109], v[170:173], v[46:49]
	v_mfma_f32_16x16x32_bf16 v[46:49], v[110:113], v[174:177], v[46:49]
	v_mfma_f32_16x16x32_bf16 v[30:33], v[106:109], v[178:181], v[30:33]
	v_mfma_f32_16x16x32_bf16 v[30:33], v[110:113], v[182:185], v[30:33]
	v_mfma_f32_16x16x32_bf16 v[14:17], v[106:109], v[186:189], v[14:17]
	v_mfma_f32_16x16x32_bf16 v[14:17], v[110:113], v[190:193], v[14:17]
	v_mfma_f32_16x16x32_bf16 v[10:13], v[122:125], v[186:189], v[10:13]
	v_mfma_f32_16x16x32_bf16 v[10:13], v[134:137], v[190:193], v[10:13]
	v_mfma_f32_16x16x32_bf16 v[26:29], v[122:125], v[178:181], v[26:29]
	v_mfma_f32_16x16x32_bf16 v[26:29], v[134:137], v[182:185], v[26:29]
	v_mfma_f32_16x16x32_bf16 v[42:45], v[122:125], v[170:173], v[42:45]
	v_mfma_f32_16x16x32_bf16 v[42:45], v[134:137], v[174:177], v[42:45]
	v_mfma_f32_16x16x32_bf16 v[58:61], v[122:125], v[162:165], v[58:61]
	v_mfma_f32_16x16x32_bf16 v[58:61], v[134:137], v[166:169], v[58:61]
	s_setprio 0
	s_setprio 1
	v_mfma_f32_16x16x32_bf16 v[54:57], v[146:149], v[162:165], v[54:57]
	v_mfma_f32_16x16x32_bf16 v[54:57], v[150:153], v[166:169], v[54:57]
	v_mfma_f32_16x16x32_bf16 v[38:41], v[146:149], v[170:173], v[38:41]
	v_mfma_f32_16x16x32_bf16 v[38:41], v[150:153], v[174:177], v[38:41]
	v_mfma_f32_16x16x32_bf16 v[22:25], v[146:149], v[178:181], v[22:25]
	v_mfma_f32_16x16x32_bf16 v[22:25], v[150:153], v[182:185], v[22:25]
	v_mfma_f32_16x16x32_bf16 v[6:9], v[146:149], v[186:189], v[6:9]
	v_mfma_f32_16x16x32_bf16 v[6:9], v[150:153], v[190:193], v[6:9]
	v_mfma_f32_16x16x32_bf16 v[2:5], v[154:157], v[186:189], v[2:5]
	v_mfma_f32_16x16x32_bf16 v[2:5], v[158:161], v[190:193], v[2:5]
	v_mfma_f32_16x16x32_bf16 v[18:21], v[154:157], v[178:181], v[18:21]
	v_mfma_f32_16x16x32_bf16 v[18:21], v[158:161], v[182:185], v[18:21]
	v_mfma_f32_16x16x32_bf16 v[34:37], v[154:157], v[170:173], v[34:37]
	v_mfma_f32_16x16x32_bf16 v[34:37], v[158:161], v[174:177], v[34:37]
	v_mfma_f32_16x16x32_bf16 v[50:53], v[154:157], v[162:165], v[50:53]
	v_mfma_f32_16x16x32_bf16 v[50:53], v[158:161], v[166:169], v[50:53]
	s_setprio 0
	s_barrier
	s_add_i32 s52, s52, 2
	s_add_u32 s26, s26, 0x100
	s_addc_u32 s27, s27, 0
	s_add_u32 s50, s50, 0x100
	s_addc_u32 s51, s51, 0
	s_cmp_gt_u32 s52, 29
	s_cbranch_scc0 .LBB0_833
	s_and_b64 vcc, exec, s[16:17]
	s_cbranch_vccz .LBB0_836
	s_barrier

; #define PG8_STAGE(bufoff, gbase, voff) do { _Pragma("unroll") for (int _i = 0; _i < 2; ++_i) \
;         __builtin_amdgcn_global_load_lds((const unsigned*)((const char*)(gbase) + (voff)[_i]), (LAS unsigned*)(lds + (bufoff) + ldsw + _i * 8192), 16, 0, 0); } while (0)
; #define PG8_LDA(dst, b, h) do { _Pragma("unroll") for (int m = 0; m < 4; ++m) _Pragma("unroll") for (int k = 0; k < 2; ++k) dst[m][k] = *(const LAS bf16x8*)(lds + PG8_SA(b, h) + aoff + m * 2048 + k * 1024); } while (0)
; #define PG8_LDB(dst, b, h) do { _Pragma("unroll") for (int n = 0; n < 2; ++n) _Pragma("unroll") for (int k = 0; k < 2; ++k) dst[n][k] = *(const LAS bf16x8*)(lds + PG8_SB(b, h) + boff + n * 2048 + k * 1024); } while (0)
; #define PG8_MMA(ai, bj, At, Bt) do { __builtin_amdgcn_s_setprio(1); _Pragma("unroll") for (int m = 0; m < 4; ++m) _Pragma("unroll") for (int n = 0; n < 2; ++n) _Pragma("unroll") for (int k = 0; k < 2; ++k) \
;         acc[ai][bj][m][n] = __builtin_amdgcn_mfma_f32_16x16x32_bf16(Bt[n][k], At[m][k], acc[ai][bj][m][n], 0, 0, 0); __builtin_amdgcn_s_setprio(0); } while (0)
; #define PG8_WAIT_V(n) asm volatile("s_waitcnt vmcnt(" #n ")" ::: "memory")
; #define PG8_WAIT_L(n) asm volatile("s_waitcnt lgkmcnt(" #n ")" ::: "memory")
; #define PG8_BAR __builtin_amdgcn_s_barrier()
; #define PG8_SCHED __builtin_amdgcn_sched_barrier(0)
; template <class Epi, class Sched, bool ALIGN_EPI = false, bool SP2 = false>
; __device__ __forceinline__ void gemm_phase(LAS unsigned char* lds, const Gemm g, const Sched& S, const Epi& E) {
;     ...
;             PG8_LDB(B0, 0, 0); PG8_LDB(B1, 0, 1); PG8_SCHED; PG8_LDA(At, 0, 0); PG8_STAGE(PG8_SA(1, 1), a1 + hstep, voffA);
;             PG8_WAIT_V(8); PG8_WAIT_L(0); PG8_BAR; PG8_MMA(0, 0, At, B0); PG8_MMA(0, 1, At, B1); PG8_BAR; PG8_SCHED;
;             PG8_LDA(At, 0, 1); PG8_STAGE(PG8_SB(0, 0), b2, voffB); PG8_STAGE(PG8_SB(0, 1), b2 + hstep, voffB); PG8_STAGE(PG8_SA(0, 0), a2, voffA);
;             PG8_WAIT_V(8); PG8_WAIT_L(0); PG8_BAR; PG8_MMA(1, 0, At, B0); PG8_MMA(1, 1, At, B1); PG8_BAR; PG8_SCHED;
.LBB0_924:
	s_add_u32 s28, s26, 0xfff80080
	s_addc_u32 s29, s27, -1
	s_add_i32 s51, 0, 0x10000
	s_cmp_eq_u32 s50, 28
	s_cselect_b32 s31, s7, s29
	s_cselect_b32 s30, s8, s28
	v_add_u32_e32 v148, s51, v151
	s_cselect_b32 s29, s19, s49
	s_cselect_b32 s28, s21, s35
	s_add_i32 s54, 0, 0x14000
	ds_read_b128 v[140:143], v148
	ds_read_b128 v[144:147], v148 offset:1024
	ds_read_b128 v[156:159], v148 offset:2048
	ds_read_b128 v[160:163], v148 offset:3072
	v_add_u32_e32 v148, s54, v151
	ds_read_b128 v[164:167], v148
	ds_read_b128 v[168:171], v148 offset:1024
	ds_read_b128 v[172:175], v148 offset:2048
	ds_read_b128 v[176:179], v148 offset:3072
	v_lshl_add_u64 v[212:213], s[26:27], 0, v[136:137]
	s_add_i32 m0, s42, 0xc000
	ds_read_b128 v[180:183], v155
	ds_read_b128 v[184:187], v155 offset:1024
	ds_read_b128 v[188:191], v155 offset:2048
	ds_read_b128 v[192:195], v155 offset:3072
	ds_read_b128 v[196:199], v155 offset:4096
	ds_read_b128 v[200:203], v155 offset:5120
	ds_read_b128 v[204:207], v155 offset:6144
	ds_read_b128 v[208:211], v155 offset:7168
	global_load_lds_dwordx4 v[212:213], off
	v_lshl_add_u64 v[212:213], s[26:27], 0, v[138:139]
	s_add_i32 m0, s42, 0xe000
	s_nop 0
	global_load_lds_dwordx4 v[212:213], off
	s_waitcnt vmcnt(8)
	s_waitcnt lgkmcnt(0)
	s_barrier
	s_setprio 1
	s_waitcnt lgkmcnt(0)
	v_mfma_f32_16x16x32_bf16 v[126:129], v[140:143], v[180:183], v[126:129]
	v_mfma_f32_16x16x32_bf16 v[126:129], v[144:147], v[184:187], v[126:129]
	v_mfma_f32_16x16x32_bf16 v[110:113], v[140:143], v[188:191], v[110:113]
	v_mfma_f32_16x16x32_bf16 v[110:113], v[144:147], v[192:195], v[110:113]
	v_mfma_f32_16x16x32_bf16 v[94:97], v[140:143], v[196:199], v[94:97]
	v_mfma_f32_16x16x32_bf16 v[94:97], v[144:147], v[200:203], v[94:97]
	v_mfma_f32_16x16x32_bf16 v[78:81], v[140:143], v[204:207], v[78:81]
	v_mfma_f32_16x16x32_bf16 v[78:81], v[144:147], v[208:211], v[78:81]
	v_mfma_f32_16x16x32_bf16 v[74:77], v[156:159], v[204:207], v[74:77]
	v_mfma_f32_16x16x32_bf16 v[74:77], v[160:163], v[208:211], v[74:77]
	v_mfma_f32_16x16x32_bf16 v[90:93], v[156:159], v[196:199], v[90:93]
	v_mfma_f32_16x16x32_bf16 v[90:93], v[160:163], v[200:203], v[90:93]
	v_mfma_f32_16x16x32_bf16 v[106:109], v[156:159], v[188:191], v[106:109]
	v_mfma_f32_16x16x32_bf16 v[106:109], v[160:163], v[192:195], v[106:109]
	v_mfma_f32_16x16x32_bf16 v[122:125], v[156:159], v[180:183], v[122:125]
	v_mfma_f32_16x16x32_bf16 v[122:125], v[160:163], v[184:187], v[122:125]
	s_setprio 0
	s_setprio 1
	v_mfma_f32_16x16x32_bf16 v[118:121], v[164:167], v[180:183], v[118:121]
	v_mfma_f32_16x16x32_bf16 v[118:121], v[168:171], v[184:187], v[118:121]
	v_mfma_f32_16x16x32_bf16 v[102:105], v[164:167], v[188:191], v[102:105]
	v_mfma_f32_16x16x32_bf16 v[102:105], v[168:171], v[192:195], v[102:105]
	v_mfma_f32_16x16x32_bf16 v[86:89], v[164:167], v[196:199], v[86:89]
	v_mfma_f32_16x16x32_bf16 v[86:89], v[168:171], v[200:203], v[86:89]
	v_mfma_f32_16x16x32_bf16 v[70:73], v[164:167], v[204:207], v[70:73]
	v_mfma_f32_16x16x32_bf16 v[70:73], v[168:171], v[208:211], v[70:73]
	v_mfma_f32_16x16x32_bf16 v[66:69], v[172:175], v[204:207], v[66:69]
	v_mfma_f32_16x16x32_bf16 v[66:69], v[176:179], v[208:211], v[66:69]
	v_mfma_f32_16x16x32_bf16 v[82:85], v[172:175], v[196:199], v[82:85]
	v_mfma_f32_16x16x32_bf16 v[82:85], v[176:179], v[200:203], v[82:85]
	v_mfma_f32_16x16x32_bf16 v[98:101], v[172:175], v[188:191], v[98:101]
	v_mfma_f32_16x16x32_bf16 v[98:101], v[176:179], v[192:195], v[98:101]
	v_mfma_f32_16x16x32_bf16 v[114:117], v[172:175], v[180:183], v[114:117]
	v_mfma_f32_16x16x32_bf16 v[114:117], v[176:179], v[184:187], v[114:117]
	s_setprio 0
	s_barrier
	s_add_i32 s51, s51, s41
	v_lshl_add_u64 v[212:213], s[28:29], 0, v[0:1]
	s_mov_b32 m0, s51
	ds_read_b128 v[180:183], v155 offset:16384
	ds_read_b128 v[184:187], v155 offset:17408
	ds_read_b128 v[188:191], v155 offset:18432
	ds_read_b128 v[192:195], v155 offset:19456
	ds_read_b128 v[196:199], v155 offset:20480
	ds_read_b128 v[200:203], v155 offset:21504
	ds_read_b128 v[204:207], v155 offset:22528
	ds_read_b128 v[208:211], v155 offset:23552
	global_load_lds_dwordx4 v[212:213], off
	s_add_i32 m0, s51, 0x2000
	s_add_u32 s52, s28, 0x80000
	v_lshl_add_u64 v[214:215], s[28:29], 0, v[130:131]
	s_addc_u32 s53, s29, 0
	s_add_i32 s51, s54, s41
	global_load_lds_dwordx4 v[214:215], off
	v_lshl_add_u64 v[216:217], s[52:53], 0, v[0:1]
	s_mov_b32 m0, s51
	v_lshl_add_u64 v[218:219], s[30:31], 0, v[132:133]
	global_load_lds_dwordx4 v[216:217], off
	v_lshl_add_u64 v[216:217], s[52:53], 0, v[130:131]
	s_add_i32 m0, s51, 0x2000
	s_nop 0
	global_load_lds_dwordx4 v[216:217], off
	v_lshl_add_u64 v[216:217], s[30:31], 0, v[134:135]
	s_mov_b32 m0, s42
	s_nop 0
	global_load_lds_dwordx4 v[216:217], off
	s_mov_b32 m0, s43
	s_nop 0
	global_load_lds_dwordx4 v[218:219], off
	s_waitcnt vmcnt(8)
	s_waitcnt lgkmcnt(0)
	s_barrier
; #define PG8_STAGE(bufoff, gbase, voff) do { _Pragma("unroll") for (int _i = 0; _i < 2; ++_i) \
;         __builtin_amdgcn_global_load_lds((const unsigned*)((const char*)(gbase) + (voff)[_i]), (LAS unsigned*)(lds + (bufoff) + ldsw + _i * 8192), 16, 0, 0); } while (0)
; #define PG8_LDA(dst, b, h) do { _Pragma("unroll") for (int m = 0; m < 4; ++m) _Pragma("unroll") for (int k = 0; k < 2; ++k) dst[m][k] = *(const LAS bf16x8*)(lds + PG8_SA(b, h) + aoff + m * 2048 + k * 1024); } while (0)
; #define PG8_LDB(dst, b, h) do { _Pragma("unroll") for (int n = 0; n < 2; ++n) _Pragma("unroll") for (int k = 0; k < 2; ++k) dst[n][k] = *(const LAS bf16x8*)(lds + PG8_SB(b, h) + boff + n * 2048 + k * 1024); } while (0)
; #define PG8_MMA(ai, bj, At, Bt) do { __builtin_amdgcn_s_setprio(1); _Pragma("unroll") for (int m = 0; m < 4; ++m) _Pragma("unroll") for (int n = 0; n < 2; ++n) _Pragma("unroll") for (int k = 0; k < 2; ++k) \
;         acc[ai][bj][m][n] = __builtin_amdgcn_mfma_f32_16x16x32_bf16(Bt[n][k], At[m][k], acc[ai][bj][m][n], 0, 0, 0); __builtin_amdgcn_s_setprio(0); } while (0)
; #define PG8_WAIT_V(n) asm volatile("s_waitcnt vmcnt(" #n ")" ::: "memory")
; #define PG8_WAIT_L(n) asm volatile("s_waitcnt lgkmcnt(" #n ")" ::: "memory")
; #define PG8_BAR __builtin_amdgcn_s_barrier()
; #define PG8_SCHED __builtin_amdgcn_sched_barrier(0)
; template <class Epi, class Sched, bool ALIGN_EPI = false, bool SP2 = false>
; __device__ __forceinline__ void gemm_phase(LAS unsigned char* lds, const Gemm g, const Sched& S, const Epi& E) {
;     ...
;             PG8_WAIT_V(8); PG8_WAIT_L(0); PG8_BAR; PG8_MMA(1, 0, At, B0); PG8_MMA(1, 1, At, B1); PG8_BAR; PG8_SCHED;
;             PG8_LDB(B0, 1, 0); PG8_LDB(B1, 1, 1); PG8_SCHED; PG8_LDA(At, 1, 0); PG8_STAGE(PG8_SA(0, 1), a2 + hstep, voffA);
;             PG8_WAIT_V(8); PG8_WAIT_L(0); PG8_BAR; PG8_MMA(0, 0, At, B0); PG8_MMA(0, 1, At, B1); PG8_BAR; PG8_SCHED;
	s_setprio 1
	s_waitcnt lgkmcnt(0)
	v_mfma_f32_16x16x32_bf16 v[62:65], v[140:143], v[180:183], v[62:65]
	v_mfma_f32_16x16x32_bf16 v[62:65], v[144:147], v[184:187], v[62:65]
	v_mfma_f32_16x16x32_bf16 v[46:49], v[140:143], v[188:191], v[46:49]
	v_mfma_f32_16x16x32_bf16 v[46:49], v[144:147], v[192:195], v[46:49]
	v_mfma_f32_16x16x32_bf16 v[30:33], v[140:143], v[196:199], v[30:33]
	v_mfma_f32_16x16x32_bf16 v[30:33], v[144:147], v[200:203], v[30:33]
	v_mfma_f32_16x16x32_bf16 v[14:17], v[140:143], v[204:207], v[14:17]
	v_mfma_f32_16x16x32_bf16 v[14:17], v[144:147], v[208:211], v[14:17]
	v_mfma_f32_16x16x32_bf16 v[10:13], v[156:159], v[204:207], v[10:13]
	v_mfma_f32_16x16x32_bf16 v[10:13], v[160:163], v[208:211], v[10:13]
	v_mfma_f32_16x16x32_bf16 v[26:29], v[156:159], v[196:199], v[26:29]
	v_mfma_f32_16x16x32_bf16 v[26:29], v[160:163], v[200:203], v[26:29]
	v_mfma_f32_16x16x32_bf16 v[42:45], v[156:159], v[188:191], v[42:45]
	v_mfma_f32_16x16x32_bf16 v[42:45], v[160:163], v[192:195], v[42:45]
	v_mfma_f32_16x16x32_bf16 v[58:61], v[156:159], v[180:183], v[58:61]
	v_mfma_f32_16x16x32_bf16 v[58:61], v[160:163], v[184:187], v[58:61]
	s_setprio 0
	s_setprio 1
	v_mfma_f32_16x16x32_bf16 v[54:57], v[164:167], v[180:183], v[54:57]
	v_mfma_f32_16x16x32_bf16 v[54:57], v[168:171], v[184:187], v[54:57]
	v_mfma_f32_16x16x32_bf16 v[38:41], v[164:167], v[188:191], v[38:41]
	v_mfma_f32_16x16x32_bf16 v[38:41], v[168:171], v[192:195], v[38:41]
	v_mfma_f32_16x16x32_bf16 v[22:25], v[164:167], v[196:199], v[22:25]
	v_mfma_f32_16x16x32_bf16 v[22:25], v[168:171], v[200:203], v[22:25]
	v_mfma_f32_16x16x32_bf16 v[6:9], v[164:167], v[204:207], v[6:9]
	v_mfma_f32_16x16x32_bf16 v[6:9], v[168:171], v[208:211], v[6:9]
	v_mfma_f32_16x16x32_bf16 v[2:5], v[172:175], v[204:207], v[2:5]
	v_mfma_f32_16x16x32_bf16 v[2:5], v[176:179], v[208:211], v[2:5]
	v_mfma_f32_16x16x32_bf16 v[18:21], v[172:175], v[196:199], v[18:21]
	v_mfma_f32_16x16x32_bf16 v[18:21], v[176:179], v[200:203], v[18:21]
	v_mfma_f32_16x16x32_bf16 v[34:37], v[172:175], v[188:191], v[34:37]
	v_mfma_f32_16x16x32_bf16 v[34:37], v[176:179], v[192:195], v[34:37]
	v_mfma_f32_16x16x32_bf16 v[50:53], v[172:175], v[180:183], v[50:53]
	v_mfma_f32_16x16x32_bf16 v[50:53], v[176:179], v[184:187], v[50:53]
	s_setprio 0
	s_barrier
	s_add_i32 s51, 0, 0x18000
	v_add_u32_e32 v148, s51, v151
	s_add_i32 s52, 0, 0x1c000
	ds_read_b128 v[140:143], v148
	ds_read_b128 v[144:147], v148 offset:1024
	ds_read_b128 v[156:159], v148 offset:2048
	ds_read_b128 v[160:163], v148 offset:3072
	v_add_u32_e32 v148, s52, v151
	ds_read_b128 v[164:167], v148
	ds_read_b128 v[168:171], v148 offset:1024
	ds_read_b128 v[172:175], v148 offset:2048
	ds_read_b128 v[176:179], v148 offset:3072
	s_add_u32 s30, s30, 0x80000
	s_addc_u32 s31, s31, 0
	s_mov_b32 m0, s44
	v_lshl_add_u64 v[220:221], s[30:31], 0, v[134:135]
	ds_read_b128 v[180:183], v155 offset:32768
	ds_read_b128 v[184:187], v155 offset:33792
	ds_read_b128 v[188:191], v155 offset:34816
	ds_read_b128 v[192:195], v155 offset:35840
	ds_read_b128 v[196:199], v155 offset:36864
	ds_read_b128 v[200:203], v155 offset:37888
	ds_read_b128 v[204:207], v155 offset:38912
	ds_read_b128 v[208:211], v155 offset:39936
	global_load_lds_dwordx4 v[220:221], off
	v_lshl_add_u64 v[220:221], s[30:31], 0, v[132:133]
	s_mov_b32 m0, s45
	s_nop 0
	global_load_lds_dwordx4 v[220:221], off
	s_waitcnt vmcnt(8)
	s_waitcnt lgkmcnt(0)
	s_barrier
	s_setprio 1
	s_waitcnt lgkmcnt(0)
	v_mfma_f32_16x16x32_bf16 v[126:129], v[140:143], v[180:183], v[126:129]
	v_mfma_f32_16x16x32_bf16 v[126:129], v[144:147], v[184:187], v[126:129]
	v_mfma_f32_16x16x32_bf16 v[110:113], v[140:143], v[188:191], v[110:113]
	v_mfma_f32_16x16x32_bf16 v[110:113], v[144:147], v[192:195], v[110:113]
	v_mfma_f32_16x16x32_bf16 v[94:97], v[140:143], v[196:199], v[94:97]
	v_mfma_f32_16x16x32_bf16 v[94:97], v[144:147], v[200:203], v[94:97]
	v_mfma_f32_16x16x32_bf16 v[78:81], v[140:143], v[204:207], v[78:81]
	v_mfma_f32_16x16x32_bf16 v[78:81], v[144:147], v[208:211], v[78:81]
	v_mfma_f32_16x16x32_bf16 v[74:77], v[156:159], v[204:207], v[74:77]
	v_mfma_f32_16x16x32_bf16 v[74:77], v[160:163], v[208:211], v[74:77]
	v_mfma_f32_16x16x32_bf16 v[90:93], v[156:159], v[196:199], v[90:93]
	v_mfma_f32_16x16x32_bf16 v[90:93], v[160:163], v[200:203], v[90:93]
	v_mfma_f32_16x16x32_bf16 v[106:109], v[156:159], v[188:191], v[106:109]
	v_mfma_f32_16x16x32_bf16 v[106:109], v[160:163], v[192:195], v[106:109]
	v_mfma_f32_16x16x32_bf16 v[122:125], v[156:159], v[180:183], v[122:125]
	v_mfma_f32_16x16x32_bf16 v[122:125], v[160:163], v[184:187], v[122:125]
	s_setprio 0
	s_setprio 1
	v_mfma_f32_16x16x32_bf16 v[118:121], v[164:167], v[180:183], v[118:121]
	v_mfma_f32_16x16x32_bf16 v[118:121], v[168:171], v[184:187], v[118:121]
	v_mfma_f32_16x16x32_bf16 v[102:105], v[164:167], v[188:191], v[102:105]
	v_mfma_f32_16x16x32_bf16 v[102:105], v[168:171], v[192:195], v[102:105]
	v_mfma_f32_16x16x32_bf16 v[86:89], v[164:167], v[196:199], v[86:89]
	v_mfma_f32_16x16x32_bf16 v[86:89], v[168:171], v[200:203], v[86:89]
	v_mfma_f32_16x16x32_bf16 v[70:73], v[164:167], v[204:207], v[70:73]
	v_mfma_f32_16x16x32_bf16 v[70:73], v[168:171], v[208:211], v[70:73]
	v_mfma_f32_16x16x32_bf16 v[66:69], v[172:175], v[204:207], v[66:69]
	v_mfma_f32_16x16x32_bf16 v[66:69], v[176:179], v[208:211], v[66:69]
	v_mfma_f32_16x16x32_bf16 v[82:85], v[172:175], v[196:199], v[82:85]
	v_mfma_f32_16x16x32_bf16 v[82:85], v[176:179], v[200:203], v[82:85]
	v_mfma_f32_16x16x32_bf16 v[98:101], v[172:175], v[188:191], v[98:101]
	v_mfma_f32_16x16x32_bf16 v[98:101], v[176:179], v[192:195], v[98:101]
	v_mfma_f32_16x16x32_bf16 v[114:117], v[172:175], v[180:183], v[114:117]
	v_mfma_f32_16x16x32_bf16 v[114:117], v[176:179], v[184:187], v[114:117]
	s_setprio 0
	s_barrier
; #define PG8_STAGE(bufoff, gbase, voff) do { _Pragma("unroll") for (int _i = 0; _i < 2; ++_i) \
;         __builtin_amdgcn_global_load_lds((const unsigned*)((const char*)(gbase) + (voff)[_i]), (LAS unsigned*)(lds + (bufoff) + ldsw + _i * 8192), 16, 0, 0); } while (0)
; #define PG8_LDA(dst, b, h) do { _Pragma("unroll") for (int m = 0; m < 4; ++m) _Pragma("unroll") for (int k = 0; k < 2; ++k) dst[m][k] = *(const LAS bf16x8*)(lds + PG8_SA(b, h) + aoff + m * 2048 + k * 1024); } while (0)
; #define PG8_MMA(ai, bj, At, Bt) do { __builtin_amdgcn_s_setprio(1); _Pragma("unroll") for (int m = 0; m < 4; ++m) _Pragma("unroll") for (int n = 0; n < 2; ++n) _Pragma("unroll") for (int k = 0; k < 2; ++k) \
;         acc[ai][bj][m][n] = __builtin_amdgcn_mfma_f32_16x16x32_bf16(Bt[n][k], At[m][k], acc[ai][bj][m][n], 0, 0, 0); __builtin_amdgcn_s_setprio(0); } while (0)
; #define PG8_WAIT_V(n) asm volatile("s_waitcnt vmcnt(" #n ")" ::: "memory")
; #define PG8_WAIT_L(n) asm volatile("s_waitcnt lgkmcnt(" #n ")" ::: "memory")
; #define PG8_BAR __builtin_amdgcn_s_barrier()
; #define PG8_SCHED __builtin_amdgcn_sched_barrier(0)
; template <class Epi, class Sched, bool ALIGN_EPI = false, bool SP2 = false>
; __device__ __forceinline__ void gemm_phase(LAS unsigned char* lds, const Gemm g, const Sched& S, const Epi& E) {
;     ...
;         for (int t = 0; t < nt; t += 2) {
;             const bool last = (t == nt - 2);
;             const char* a1 = cA + (size_t)(t + 1) * kstep;
;             const char* a2 = last ? nA : cA + (size_t)(t + 2) * kstep; const char* b2 = last ? nB : cB + (size_t)(t + 2) * kstep;
;     ...
;             PG8_LDA(At, 1, 1); PG8_STAGE(PG8_SB(1, 0), b3, voffB); PG8_STAGE(PG8_SB(1, 1), b3 + hstep, voffB); PG8_STAGE(PG8_SA(1, 0), a3, voffA);
;             PG8_WAIT_V(8); PG8_WAIT_L(0); PG8_BAR; PG8_MMA(1, 0, At, B0); PG8_MMA(1, 1, At, B1); PG8_BAR; PG8_SCHED;
	s_add_i32 s30, s51, s41
	v_lshl_add_u64 v[212:213], v[212:213], 0, s[12:13]
	s_mov_b32 m0, s30
	ds_read_b128 v[180:183], v155 offset:49152
	ds_read_b128 v[184:187], v155 offset:50176
	ds_read_b128 v[188:191], v155 offset:51200
	ds_read_b128 v[192:195], v155 offset:52224
	ds_read_b128 v[196:199], v155 offset:53248
	ds_read_b128 v[200:203], v155 offset:54272
	ds_read_b128 v[204:207], v155 offset:55296
	ds_read_b128 v[208:211], v155 offset:56320
	global_load_lds_dwordx4 v[212:213], off
	s_add_i32 m0, s30, 0x2000
	s_add_u32 s28, s28, 0x80080
	v_lshl_add_u64 v[212:213], v[214:215], 0, s[12:13]
	s_addc_u32 s29, s29, 0
	s_add_i32 s30, s52, s41
	global_load_lds_dwordx4 v[212:213], off
	v_lshl_add_u64 v[212:213], s[28:29], 0, v[0:1]
	s_mov_b32 m0, s30
	s_nop 0
	global_load_lds_dwordx4 v[212:213], off
	v_lshl_add_u64 v[212:213], s[28:29], 0, v[130:131]
	s_add_i32 m0, s30, 0x2000
	s_nop 0
	global_load_lds_dwordx4 v[212:213], off
	v_lshl_add_u64 v[212:213], v[216:217], 0, s[12:13]
	s_mov_b32 m0, s46
	s_nop 0
	global_load_lds_dwordx4 v[212:213], off
	v_lshl_add_u64 v[212:213], v[218:219], 0, s[12:13]
	s_mov_b32 m0, s47
	s_nop 0
	global_load_lds_dwordx4 v[212:213], off
	s_waitcnt vmcnt(8)
	s_waitcnt lgkmcnt(0)
	s_barrier
	s_setprio 1
	s_waitcnt lgkmcnt(0)
	v_mfma_f32_16x16x32_bf16 v[62:65], v[140:143], v[180:183], v[62:65]
	v_mfma_f32_16x16x32_bf16 v[62:65], v[144:147], v[184:187], v[62:65]
	v_mfma_f32_16x16x32_bf16 v[46:49], v[140:143], v[188:191], v[46:49]
	v_mfma_f32_16x16x32_bf16 v[46:49], v[144:147], v[192:195], v[46:49]
	v_mfma_f32_16x16x32_bf16 v[30:33], v[140:143], v[196:199], v[30:33]
	v_mfma_f32_16x16x32_bf16 v[30:33], v[144:147], v[200:203], v[30:33]
	v_mfma_f32_16x16x32_bf16 v[14:17], v[140:143], v[204:207], v[14:17]
	v_mfma_f32_16x16x32_bf16 v[14:17], v[144:147], v[208:211], v[14:17]
	v_mfma_f32_16x16x32_bf16 v[10:13], v[156:159], v[204:207], v[10:13]
	v_mfma_f32_16x16x32_bf16 v[10:13], v[160:163], v[208:211], v[10:13]
	v_mfma_f32_16x16x32_bf16 v[26:29], v[156:159], v[196:199], v[26:29]
	v_mfma_f32_16x16x32_bf16 v[26:29], v[160:163], v[200:203], v[26:29]
	v_mfma_f32_16x16x32_bf16 v[42:45], v[156:159], v[188:191], v[42:45]
	v_mfma_f32_16x16x32_bf16 v[42:45], v[160:163], v[192:195], v[42:45]
	v_mfma_f32_16x16x32_bf16 v[58:61], v[156:159], v[180:183], v[58:61]
	v_mfma_f32_16x16x32_bf16 v[58:61], v[160:163], v[184:187], v[58:61]
	s_setprio 0
	s_setprio 1
	v_mfma_f32_16x16x32_bf16 v[54:57], v[164:167], v[180:183], v[54:57]
	v_mfma_f32_16x16x32_bf16 v[54:57], v[168:171], v[184:187], v[54:57]
	v_mfma_f32_16x16x32_bf16 v[38:41], v[164:167], v[188:191], v[38:41]
	v_mfma_f32_16x16x32_bf16 v[38:41], v[168:171], v[192:195], v[38:41]
	v_mfma_f32_16x16x32_bf16 v[22:25], v[164:167], v[196:199], v[22:25]
	v_mfma_f32_16x16x32_bf16 v[22:25], v[168:171], v[200:203], v[22:25]
	v_mfma_f32_16x16x32_bf16 v[6:9], v[164:167], v[204:207], v[6:9]
	v_mfma_f32_16x16x32_bf16 v[6:9], v[168:171], v[208:211], v[6:9]
	v_mfma_f32_16x16x32_bf16 v[2:5], v[172:175], v[204:207], v[2:5]
	v_mfma_f32_16x16x32_bf16 v[2:5], v[176:179], v[208:211], v[2:5]
	v_mfma_f32_16x16x32_bf16 v[18:21], v[172:175], v[196:199], v[18:21]
	v_mfma_f32_16x16x32_bf16 v[18:21], v[176:179], v[200:203], v[18:21]
	v_mfma_f32_16x16x32_bf16 v[34:37], v[172:175], v[188:191], v[34:37]
	v_mfma_f32_16x16x32_bf16 v[34:37], v[176:179], v[192:195], v[34:37]
	v_mfma_f32_16x16x32_bf16 v[50:53], v[172:175], v[180:183], v[50:53]
	v_mfma_f32_16x16x32_bf16 v[50:53], v[176:179], v[184:187], v[50:53]
	s_setprio 0
	s_barrier
	s_add_i32 s50, s50, 2
	s_add_u32 s26, s26, 0x100
	s_addc_u32 s27, s27, 0
	s_add_u32 s35, s35, 0x100
	s_addc_u32 s49, s49, 0
	s_cmp_gt_u32 s50, 29
	s_cbranch_scc0 .LBB0_924
	s_and_b64 vcc, exec, s[16:17]
	s_cbranch_vccz .LBB0_927
	s_barrier

; #define PG8_STAGE(bufoff, gbase, voff) do { _Pragma("unroll") for (int _i = 0; _i < 2; ++_i) \
;         __builtin_amdgcn_global_load_lds((const unsigned*)((const char*)(gbase) + (voff)[_i]), (LAS unsigned*)(lds + (bufoff) + ldsw + _i * 8192), 16, 0, 0); } while (0)
; #define PG8_LDA(dst, b, h) do { _Pragma("unroll") for (int m = 0; m < 4; ++m) _Pragma("unroll") for (int k = 0; k < 2; ++k) dst[m][k] = *(const LAS bf16x8*)(lds + PG8_SA(b, h) + aoff + m * 2048 + k * 1024); } while (0)
; #define PG8_LDB(dst, b, h) do { _Pragma("unroll") for (int n = 0; n < 2; ++n) _Pragma("unroll") for (int k = 0; k < 2; ++k) dst[n][k] = *(const LAS bf16x8*)(lds + PG8_SB(b, h) + boff + n * 2048 + k * 1024); } while (0)
; #define PG8_MMA(ai, bj, At, Bt) do { __builtin_amdgcn_s_setprio(1); _Pragma("unroll") for (int m = 0; m < 4; ++m) _Pragma("unroll") for (int n = 0; n < 2; ++n) _Pragma("unroll") for (int k = 0; k < 2; ++k) \
;         acc[ai][bj][m][n] = __builtin_amdgcn_mfma_f32_16x16x32_bf16(Bt[n][k], At[m][k], acc[ai][bj][m][n], 0, 0, 0); __builtin_amdgcn_s_setprio(0); } while (0)
; #define PG8_WAIT_V(n) asm volatile("s_waitcnt vmcnt(" #n ")" ::: "memory")
; #define PG8_WAIT_L(n) asm volatile("s_waitcnt lgkmcnt(" #n ")" ::: "memory")
; #define PG8_BAR __builtin_amdgcn_s_barrier()
; #define PG8_SCHED __builtin_amdgcn_sched_barrier(0)
; template <class Epi, class Sched, bool ALIGN_EPI = false, bool SP2 = false>
; __device__ __forceinline__ void gemm_phase(LAS unsigned char* lds, const Gemm g, const Sched& S, const Epi& E) {
;     ...
;             PG8_LDB(B0, 0, 0); PG8_LDB(B1, 0, 1); PG8_SCHED; PG8_LDA(At, 0, 0); PG8_STAGE(PG8_SA(1, 1), a1 + hstep, voffA);
;             PG8_WAIT_V(8); PG8_WAIT_L(0); PG8_BAR; PG8_MMA(0, 0, At, B0); PG8_MMA(0, 1, At, B1); PG8_BAR; PG8_SCHED;
;             PG8_LDA(At, 0, 1); PG8_STAGE(PG8_SB(0, 0), b2, voffB); PG8_STAGE(PG8_SB(0, 1), b2 + hstep, voffB); PG8_STAGE(PG8_SA(0, 0), a2, voffA);
;             PG8_WAIT_V(8); PG8_WAIT_L(0); PG8_BAR; PG8_MMA(1, 0, At, B0); PG8_MMA(1, 1, At, B1); PG8_BAR; PG8_SCHED;
.LBB0_1007:
	s_add_u32 s24, s22, 0x100
	s_addc_u32 s25, s23, 0
	s_add_i32 s49, 0, 0x10000
	s_cmpk_eq_i32 s48, 0x54
	s_cselect_b32 s29, s1, s25
	s_cselect_b32 s28, s0, s24
	s_cselect_b32 s27, s21, s47
	s_cselect_b32 s26, s20, s46
	s_add_i32 s50, 0, 0x14000
	v_add_u32_e32 v126, s49, v247
	v_add_u32_e32 v158, s50, v247
	ds_read_b128 v[90:93], v126
	ds_read_b128 v[102:105], v126 offset:1024
	ds_read_b128 v[114:117], v126 offset:2048
	ds_read_b128 v[126:129], v126 offset:3072
	ds_read_b128 v[138:141], v158
	ds_read_b128 v[142:145], v158 offset:1024
	ds_read_b128 v[154:157], v158 offset:2048
	ds_read_b128 v[158:161], v158 offset:3072
	v_lshl_add_u64 v[204:205], s[22:23], 0, v[200:201]
	s_add_i32 m0, s8, 0xc000
	ds_read_b128 v[162:165], v249
	ds_read_b128 v[166:169], v249 offset:1024
	ds_read_b128 v[170:173], v249 offset:2048
	ds_read_b128 v[174:177], v249 offset:3072
	ds_read_b128 v[178:181], v249 offset:4096
	ds_read_b128 v[182:185], v249 offset:5120
	ds_read_b128 v[186:189], v249 offset:6144
	ds_read_b128 v[190:193], v249 offset:7168
	global_load_lds_dwordx4 v[204:205], off
	v_lshl_add_u64 v[204:205], s[22:23], 0, v[202:203]
	s_add_i32 m0, s8, 0xe000
	s_nop 0
	global_load_lds_dwordx4 v[204:205], off
	s_waitcnt vmcnt(8)
	s_waitcnt lgkmcnt(0)
	s_barrier
	s_setprio 1
	s_waitcnt lgkmcnt(0)
	v_mfma_f32_16x16x32_bf16 v[150:153], v[90:93], v[162:165], v[150:153]
	v_mfma_f32_16x16x32_bf16 v[150:153], v[102:105], v[166:169], v[150:153]
	v_mfma_f32_16x16x32_bf16 v[122:125], v[90:93], v[170:173], v[122:125]
	v_mfma_f32_16x16x32_bf16 v[122:125], v[102:105], v[174:177], v[122:125]
	v_mfma_f32_16x16x32_bf16 v[98:101], v[90:93], v[178:181], v[98:101]
	v_mfma_f32_16x16x32_bf16 v[98:101], v[102:105], v[182:185], v[98:101]
	v_mfma_f32_16x16x32_bf16 v[78:81], v[90:93], v[186:189], v[78:81]
	v_mfma_f32_16x16x32_bf16 v[78:81], v[102:105], v[190:193], v[78:81]
	v_mfma_f32_16x16x32_bf16 v[74:77], v[114:117], v[186:189], v[74:77]
	v_mfma_f32_16x16x32_bf16 v[74:77], v[126:129], v[190:193], v[74:77]
	v_mfma_f32_16x16x32_bf16 v[94:97], v[114:117], v[178:181], v[94:97]
	v_mfma_f32_16x16x32_bf16 v[94:97], v[126:129], v[182:185], v[94:97]
	v_mfma_f32_16x16x32_bf16 v[118:121], v[114:117], v[170:173], v[118:121]
	v_mfma_f32_16x16x32_bf16 v[118:121], v[126:129], v[174:177], v[118:121]
	v_mfma_f32_16x16x32_bf16 v[146:149], v[114:117], v[162:165], v[146:149]
	v_mfma_f32_16x16x32_bf16 v[146:149], v[126:129], v[166:169], v[146:149]
	s_setprio 0
	s_setprio 1
	v_mfma_f32_16x16x32_bf16 v[134:137], v[138:141], v[162:165], v[134:137]
	v_mfma_f32_16x16x32_bf16 v[134:137], v[142:145], v[166:169], v[134:137]
	v_mfma_f32_16x16x32_bf16 v[110:113], v[138:141], v[170:173], v[110:113]
	v_mfma_f32_16x16x32_bf16 v[110:113], v[142:145], v[174:177], v[110:113]
	v_mfma_f32_16x16x32_bf16 v[86:89], v[138:141], v[178:181], v[86:89]
	v_mfma_f32_16x16x32_bf16 v[86:89], v[142:145], v[182:185], v[86:89]
	v_mfma_f32_16x16x32_bf16 v[70:73], v[138:141], v[186:189], v[70:73]
	v_mfma_f32_16x16x32_bf16 v[70:73], v[142:145], v[190:193], v[70:73]
	v_mfma_f32_16x16x32_bf16 v[66:69], v[154:157], v[186:189], v[66:69]
	v_mfma_f32_16x16x32_bf16 v[66:69], v[158:161], v[190:193], v[66:69]
	v_mfma_f32_16x16x32_bf16 v[82:85], v[154:157], v[178:181], v[82:85]
	v_mfma_f32_16x16x32_bf16 v[82:85], v[158:161], v[182:185], v[82:85]
	v_mfma_f32_16x16x32_bf16 v[106:109], v[154:157], v[170:173], v[106:109]
	v_mfma_f32_16x16x32_bf16 v[106:109], v[158:161], v[174:177], v[106:109]
	v_mfma_f32_16x16x32_bf16 v[130:133], v[154:157], v[162:165], v[130:133]
	v_mfma_f32_16x16x32_bf16 v[130:133], v[158:161], v[166:169], v[130:133]
	s_setprio 0
	s_barrier
	s_add_i32 s22, s49, s7
	v_lshl_add_u64 v[204:205], s[26:27], 0, v[0:1]
	s_mov_b32 m0, s22
	ds_read_b128 v[162:165], v249 offset:16384
	ds_read_b128 v[166:169], v249 offset:17408
	ds_read_b128 v[170:173], v249 offset:18432
	ds_read_b128 v[174:177], v249 offset:19456
	ds_read_b128 v[178:181], v249 offset:20480
	ds_read_b128 v[182:185], v249 offset:21504
	ds_read_b128 v[186:189], v249 offset:22528
	ds_read_b128 v[190:193], v249 offset:23552
	global_load_lds_dwordx4 v[204:205], off
	s_add_i32 m0, s22, 0x2000
	s_add_u32 s22, s26, 0x160000
	v_lshl_add_u64 v[206:207], s[26:27], 0, v[194:195]
	s_addc_u32 s23, s27, 0
	s_add_i32 s49, s50, s7
	global_load_lds_dwordx4 v[206:207], off
	v_lshl_add_u64 v[208:209], s[22:23], 0, v[0:1]
	s_mov_b32 m0, s49
	v_lshl_add_u64 v[210:211], s[28:29], 0, v[196:197]
	global_load_lds_dwordx4 v[208:209], off
	v_lshl_add_u64 v[208:209], s[22:23], 0, v[194:195]
	s_add_i32 m0, s49, 0x2000
	s_nop 0
	global_load_lds_dwordx4 v[208:209], off
	v_lshl_add_u64 v[208:209], s[28:29], 0, v[198:199]
	s_mov_b32 m0, s8
	s_nop 0
	global_load_lds_dwordx4 v[208:209], off
	s_mov_b32 m0, s9
	s_nop 0
	global_load_lds_dwordx4 v[210:211], off
	s_waitcnt vmcnt(8)
	s_waitcnt lgkmcnt(0)
	s_barrier
; #define PG8_STAGE(bufoff, gbase, voff) do { _Pragma("unroll") for (int _i = 0; _i < 2; ++_i) \
;         __builtin_amdgcn_global_load_lds((const unsigned*)((const char*)(gbase) + (voff)[_i]), (LAS unsigned*)(lds + (bufoff) + ldsw + _i * 8192), 16, 0, 0); } while (0)
; #define PG8_LDA(dst, b, h) do { _Pragma("unroll") for (int m = 0; m < 4; ++m) _Pragma("unroll") for (int k = 0; k < 2; ++k) dst[m][k] = *(const LAS bf16x8*)(lds + PG8_SA(b, h) + aoff + m * 2048 + k * 1024); } while (0)
; #define PG8_LDB(dst, b, h) do { _Pragma("unroll") for (int n = 0; n < 2; ++n) _Pragma("unroll") for (int k = 0; k < 2; ++k) dst[n][k] = *(const LAS bf16x8*)(lds + PG8_SB(b, h) + boff + n * 2048 + k * 1024); } while (0)
; #define PG8_MMA(ai, bj, At, Bt) do { __builtin_amdgcn_s_setprio(1); _Pragma("unroll") for (int m = 0; m < 4; ++m) _Pragma("unroll") for (int n = 0; n < 2; ++n) _Pragma("unroll") for (int k = 0; k < 2; ++k) \
;         acc[ai][bj][m][n] = __builtin_amdgcn_mfma_f32_16x16x32_bf16(Bt[n][k], At[m][k], acc[ai][bj][m][n], 0, 0, 0); __builtin_amdgcn_s_setprio(0); } while (0)
; #define PG8_WAIT_V(n) asm volatile("s_waitcnt vmcnt(" #n ")" ::: "memory")
; #define PG8_WAIT_L(n) asm volatile("s_waitcnt lgkmcnt(" #n ")" ::: "memory")
; #define PG8_BAR __builtin_amdgcn_s_barrier()
; #define PG8_SCHED __builtin_amdgcn_sched_barrier(0)
; template <class Epi, class Sched, bool ALIGN_EPI = false, bool SP2 = false>
; __device__ __forceinline__ void gemm_phase(LAS unsigned char* lds, const Gemm g, const Sched& S, const Epi& E) {
;     ...
;             PG8_WAIT_V(8); PG8_WAIT_L(0); PG8_BAR; PG8_MMA(1, 0, At, B0); PG8_MMA(1, 1, At, B1); PG8_BAR; PG8_SCHED;
;             PG8_LDB(B0, 1, 0); PG8_LDB(B1, 1, 1); PG8_SCHED; PG8_LDA(At, 1, 0); PG8_STAGE(PG8_SA(0, 1), a2 + hstep, voffA);
;             PG8_WAIT_V(8); PG8_WAIT_L(0); PG8_BAR; PG8_MMA(0, 0, At, B0); PG8_MMA(0, 1, At, B1); PG8_BAR; PG8_SCHED;
	s_setprio 1
	s_waitcnt lgkmcnt(0)
	v_mfma_f32_16x16x32_bf16 v[62:65], v[90:93], v[162:165], v[62:65]
	v_mfma_f32_16x16x32_bf16 v[62:65], v[102:105], v[166:169], v[62:65]
	v_mfma_f32_16x16x32_bf16 v[46:49], v[90:93], v[170:173], v[46:49]
	v_mfma_f32_16x16x32_bf16 v[46:49], v[102:105], v[174:177], v[46:49]
	v_mfma_f32_16x16x32_bf16 v[30:33], v[90:93], v[178:181], v[30:33]
	v_mfma_f32_16x16x32_bf16 v[30:33], v[102:105], v[182:185], v[30:33]
	v_mfma_f32_16x16x32_bf16 v[14:17], v[90:93], v[186:189], v[14:17]
	v_mfma_f32_16x16x32_bf16 v[14:17], v[102:105], v[190:193], v[14:17]
	v_mfma_f32_16x16x32_bf16 v[10:13], v[114:117], v[186:189], v[10:13]
	v_mfma_f32_16x16x32_bf16 v[10:13], v[126:129], v[190:193], v[10:13]
	v_mfma_f32_16x16x32_bf16 v[26:29], v[114:117], v[178:181], v[26:29]
	v_mfma_f32_16x16x32_bf16 v[26:29], v[126:129], v[182:185], v[26:29]
	v_mfma_f32_16x16x32_bf16 v[42:45], v[114:117], v[170:173], v[42:45]
	v_mfma_f32_16x16x32_bf16 v[42:45], v[126:129], v[174:177], v[42:45]
	v_mfma_f32_16x16x32_bf16 v[58:61], v[114:117], v[162:165], v[58:61]
	v_mfma_f32_16x16x32_bf16 v[58:61], v[126:129], v[166:169], v[58:61]
	s_setprio 0
	s_setprio 1
	v_mfma_f32_16x16x32_bf16 v[54:57], v[138:141], v[162:165], v[54:57]
	v_mfma_f32_16x16x32_bf16 v[54:57], v[142:145], v[166:169], v[54:57]
	v_mfma_f32_16x16x32_bf16 v[38:41], v[138:141], v[170:173], v[38:41]
	v_mfma_f32_16x16x32_bf16 v[38:41], v[142:145], v[174:177], v[38:41]
	v_mfma_f32_16x16x32_bf16 v[22:25], v[138:141], v[178:181], v[22:25]
	v_mfma_f32_16x16x32_bf16 v[22:25], v[142:145], v[182:185], v[22:25]
	v_mfma_f32_16x16x32_bf16 v[6:9], v[138:141], v[186:189], v[6:9]
	v_mfma_f32_16x16x32_bf16 v[6:9], v[142:145], v[190:193], v[6:9]
	v_mfma_f32_16x16x32_bf16 v[2:5], v[154:157], v[186:189], v[2:5]
	v_mfma_f32_16x16x32_bf16 v[2:5], v[158:161], v[190:193], v[2:5]
	v_mfma_f32_16x16x32_bf16 v[18:21], v[154:157], v[178:181], v[18:21]
	v_mfma_f32_16x16x32_bf16 v[18:21], v[158:161], v[182:185], v[18:21]
	v_mfma_f32_16x16x32_bf16 v[34:37], v[154:157], v[170:173], v[34:37]
	v_mfma_f32_16x16x32_bf16 v[34:37], v[158:161], v[174:177], v[34:37]
	v_mfma_f32_16x16x32_bf16 v[50:53], v[154:157], v[162:165], v[50:53]
	v_mfma_f32_16x16x32_bf16 v[50:53], v[158:161], v[166:169], v[50:53]
	s_setprio 0
	s_barrier
	s_add_i32 s49, 0, 0x18000
	s_add_i32 s50, 0, 0x1c000
	v_add_u32_e32 v126, s49, v247
	v_add_u32_e32 v158, s50, v247
	ds_read_b128 v[90:93], v126
	ds_read_b128 v[102:105], v126 offset:1024
	ds_read_b128 v[114:117], v126 offset:2048
	ds_read_b128 v[126:129], v126 offset:3072
	ds_read_b128 v[138:141], v158
	ds_read_b128 v[142:145], v158 offset:1024
	ds_read_b128 v[154:157], v158 offset:2048
	ds_read_b128 v[158:161], v158 offset:3072
	s_add_u32 s22, s28, 0x160000
	s_addc_u32 s23, s29, 0
	s_mov_b32 m0, s30
	v_lshl_add_u64 v[212:213], s[22:23], 0, v[198:199]
	ds_read_b128 v[162:165], v249 offset:32768
	ds_read_b128 v[166:169], v249 offset:33792
	ds_read_b128 v[170:173], v249 offset:34816
	ds_read_b128 v[174:177], v249 offset:35840
	ds_read_b128 v[178:181], v249 offset:36864
	ds_read_b128 v[182:185], v249 offset:37888
	ds_read_b128 v[186:189], v249 offset:38912
	ds_read_b128 v[190:193], v249 offset:39936
	global_load_lds_dwordx4 v[212:213], off
	v_lshl_add_u64 v[212:213], s[22:23], 0, v[196:197]
	s_mov_b32 m0, s31
	s_nop 0
	global_load_lds_dwordx4 v[212:213], off
	s_waitcnt vmcnt(8)
	s_waitcnt lgkmcnt(0)
	s_barrier
	s_setprio 1
	s_waitcnt lgkmcnt(0)
	v_mfma_f32_16x16x32_bf16 v[150:153], v[90:93], v[162:165], v[150:153]
	v_mfma_f32_16x16x32_bf16 v[150:153], v[102:105], v[166:169], v[150:153]
	v_mfma_f32_16x16x32_bf16 v[122:125], v[90:93], v[170:173], v[122:125]
	v_mfma_f32_16x16x32_bf16 v[122:125], v[102:105], v[174:177], v[122:125]
	v_mfma_f32_16x16x32_bf16 v[98:101], v[90:93], v[178:181], v[98:101]
	v_mfma_f32_16x16x32_bf16 v[98:101], v[102:105], v[182:185], v[98:101]
	v_mfma_f32_16x16x32_bf16 v[78:81], v[90:93], v[186:189], v[78:81]
	v_mfma_f32_16x16x32_bf16 v[78:81], v[102:105], v[190:193], v[78:81]
	v_mfma_f32_16x16x32_bf16 v[74:77], v[114:117], v[186:189], v[74:77]
	v_mfma_f32_16x16x32_bf16 v[74:77], v[126:129], v[190:193], v[74:77]
	v_mfma_f32_16x16x32_bf16 v[94:97], v[114:117], v[178:181], v[94:97]
	v_mfma_f32_16x16x32_bf16 v[94:97], v[126:129], v[182:185], v[94:97]
	v_mfma_f32_16x16x32_bf16 v[118:121], v[114:117], v[170:173], v[118:121]
	v_mfma_f32_16x16x32_bf16 v[118:121], v[126:129], v[174:177], v[118:121]
	v_mfma_f32_16x16x32_bf16 v[146:149], v[114:117], v[162:165], v[146:149]
	v_mfma_f32_16x16x32_bf16 v[146:149], v[126:129], v[166:169], v[146:149]
	s_setprio 0
	s_setprio 1
	v_mfma_f32_16x16x32_bf16 v[134:137], v[138:141], v[162:165], v[134:137]
	v_mfma_f32_16x16x32_bf16 v[134:137], v[142:145], v[166:169], v[134:137]
	v_mfma_f32_16x16x32_bf16 v[110:113], v[138:141], v[170:173], v[110:113]
	v_mfma_f32_16x16x32_bf16 v[110:113], v[142:145], v[174:177], v[110:113]
	v_mfma_f32_16x16x32_bf16 v[86:89], v[138:141], v[178:181], v[86:89]
	v_mfma_f32_16x16x32_bf16 v[86:89], v[142:145], v[182:185], v[86:89]
	v_mfma_f32_16x16x32_bf16 v[70:73], v[138:141], v[186:189], v[70:73]
	v_mfma_f32_16x16x32_bf16 v[70:73], v[142:145], v[190:193], v[70:73]
	v_mfma_f32_16x16x32_bf16 v[66:69], v[154:157], v[186:189], v[66:69]
	v_mfma_f32_16x16x32_bf16 v[66:69], v[158:161], v[190:193], v[66:69]
	v_mfma_f32_16x16x32_bf16 v[82:85], v[154:157], v[178:181], v[82:85]
	v_mfma_f32_16x16x32_bf16 v[82:85], v[158:161], v[182:185], v[82:85]
	v_mfma_f32_16x16x32_bf16 v[106:109], v[154:157], v[170:173], v[106:109]
	v_mfma_f32_16x16x32_bf16 v[106:109], v[158:161], v[174:177], v[106:109]
	v_mfma_f32_16x16x32_bf16 v[130:133], v[154:157], v[162:165], v[130:133]
	v_mfma_f32_16x16x32_bf16 v[130:133], v[158:161], v[166:169], v[130:133]
	s_setprio 0
	s_barrier
; #define PG8_STAGE(bufoff, gbase, voff) do { _Pragma("unroll") for (int _i = 0; _i < 2; ++_i) \
;         __builtin_amdgcn_global_load_lds((const unsigned*)((const char*)(gbase) + (voff)[_i]), (LAS unsigned*)(lds + (bufoff) + ldsw + _i * 8192), 16, 0, 0); } while (0)
; #define PG8_LDA(dst, b, h) do { _Pragma("unroll") for (int m = 0; m < 4; ++m) _Pragma("unroll") for (int k = 0; k < 2; ++k) dst[m][k] = *(const LAS bf16x8*)(lds + PG8_SA(b, h) + aoff + m * 2048 + k * 1024); } while (0)
; #define PG8_MMA(ai, bj, At, Bt) do { __builtin_amdgcn_s_setprio(1); _Pragma("unroll") for (int m = 0; m < 4; ++m) _Pragma("unroll") for (int n = 0; n < 2; ++n) _Pragma("unroll") for (int k = 0; k < 2; ++k) \
;         acc[ai][bj][m][n] = __builtin_amdgcn_mfma_f32_16x16x32_bf16(Bt[n][k], At[m][k], acc[ai][bj][m][n], 0, 0, 0); __builtin_amdgcn_s_setprio(0); } while (0)
; #define PG8_WAIT_V(n) asm volatile("s_waitcnt vmcnt(" #n ")" ::: "memory")
; #define PG8_WAIT_L(n) asm volatile("s_waitcnt lgkmcnt(" #n ")" ::: "memory")
; #define PG8_BAR __builtin_amdgcn_s_barrier()
; #define PG8_SCHED __builtin_amdgcn_sched_barrier(0)
; template <class Epi, class Sched, bool ALIGN_EPI = false, bool SP2 = false>
; __device__ __forceinline__ void gemm_phase(LAS unsigned char* lds, const Gemm g, const Sched& S, const Epi& E) {
;     ...
;         for (int t = 0; t < nt; t += 2) {
;             const bool last = (t == nt - 2);
;             const char* a1 = cA + (size_t)(t + 1) * kstep;
;             const char* a2 = last ? nA : cA + (size_t)(t + 2) * kstep; const char* b2 = last ? nB : cB + (size_t)(t + 2) * kstep;
;     ...
;             PG8_LDA(At, 1, 1); PG8_STAGE(PG8_SB(1, 0), b3, voffB); PG8_STAGE(PG8_SB(1, 1), b3 + hstep, voffB); PG8_STAGE(PG8_SA(1, 0), a3, voffA);
;             PG8_WAIT_V(8); PG8_WAIT_L(0); PG8_BAR; PG8_MMA(1, 0, At, B0); PG8_MMA(1, 1, At, B1); PG8_BAR; PG8_SCHED;
	s_add_i32 s22, s49, s7
	v_lshl_add_u64 v[204:205], v[204:205], 0, s[12:13]
	s_mov_b32 m0, s22
	ds_read_b128 v[162:165], v249 offset:49152
	ds_read_b128 v[166:169], v249 offset:50176
	ds_read_b128 v[170:173], v249 offset:51200
	ds_read_b128 v[174:177], v249 offset:52224
	ds_read_b128 v[178:181], v249 offset:53248
	ds_read_b128 v[182:185], v249 offset:54272
	ds_read_b128 v[186:189], v249 offset:55296
	ds_read_b128 v[190:193], v249 offset:56320
	global_load_lds_dwordx4 v[204:205], off
	s_add_i32 m0, s22, 0x2000
	s_add_u32 s22, s26, 0x160080
	v_lshl_add_u64 v[204:205], v[206:207], 0, s[12:13]
	s_addc_u32 s23, s27, 0
	s_add_i32 s26, s50, s7
	global_load_lds_dwordx4 v[204:205], off
	v_lshl_add_u64 v[204:205], s[22:23], 0, v[0:1]
	s_mov_b32 m0, s26
	s_nop 0
	global_load_lds_dwordx4 v[204:205], off
	v_lshl_add_u64 v[204:205], s[22:23], 0, v[194:195]
	s_add_i32 m0, s26, 0x2000
	s_nop 0
	global_load_lds_dwordx4 v[204:205], off
	v_lshl_add_u64 v[204:205], v[208:209], 0, s[12:13]
	s_mov_b32 m0, s35
	s_nop 0
	global_load_lds_dwordx4 v[204:205], off
	v_lshl_add_u64 v[204:205], v[210:211], 0, s[12:13]
	s_mov_b32 m0, s40
	s_nop 0
	global_load_lds_dwordx4 v[204:205], off
	s_waitcnt vmcnt(8)
	s_waitcnt lgkmcnt(0)
	s_barrier
	s_setprio 1
	s_waitcnt lgkmcnt(0)
	v_mfma_f32_16x16x32_bf16 v[62:65], v[90:93], v[162:165], v[62:65]
	v_mfma_f32_16x16x32_bf16 v[62:65], v[102:105], v[166:169], v[62:65]
	v_mfma_f32_16x16x32_bf16 v[46:49], v[90:93], v[170:173], v[46:49]
	v_mfma_f32_16x16x32_bf16 v[46:49], v[102:105], v[174:177], v[46:49]
	v_mfma_f32_16x16x32_bf16 v[30:33], v[90:93], v[178:181], v[30:33]
	v_mfma_f32_16x16x32_bf16 v[30:33], v[102:105], v[182:185], v[30:33]
	v_mfma_f32_16x16x32_bf16 v[14:17], v[90:93], v[186:189], v[14:17]
	v_mfma_f32_16x16x32_bf16 v[14:17], v[102:105], v[190:193], v[14:17]
	v_mfma_f32_16x16x32_bf16 v[10:13], v[114:117], v[186:189], v[10:13]
	v_mfma_f32_16x16x32_bf16 v[10:13], v[126:129], v[190:193], v[10:13]
	v_mfma_f32_16x16x32_bf16 v[26:29], v[114:117], v[178:181], v[26:29]
	v_mfma_f32_16x16x32_bf16 v[26:29], v[126:129], v[182:185], v[26:29]
	v_mfma_f32_16x16x32_bf16 v[42:45], v[114:117], v[170:173], v[42:45]
	v_mfma_f32_16x16x32_bf16 v[42:45], v[126:129], v[174:177], v[42:45]
	v_mfma_f32_16x16x32_bf16 v[58:61], v[114:117], v[162:165], v[58:61]
	v_mfma_f32_16x16x32_bf16 v[58:61], v[126:129], v[166:169], v[58:61]
	s_setprio 0
	s_setprio 1
	v_mfma_f32_16x16x32_bf16 v[54:57], v[138:141], v[162:165], v[54:57]
	v_mfma_f32_16x16x32_bf16 v[54:57], v[142:145], v[166:169], v[54:57]
	v_mfma_f32_16x16x32_bf16 v[38:41], v[138:141], v[170:173], v[38:41]
	v_mfma_f32_16x16x32_bf16 v[38:41], v[142:145], v[174:177], v[38:41]
	v_mfma_f32_16x16x32_bf16 v[22:25], v[138:141], v[178:181], v[22:25]
	v_mfma_f32_16x16x32_bf16 v[22:25], v[142:145], v[182:185], v[22:25]
	v_mfma_f32_16x16x32_bf16 v[6:9], v[138:141], v[186:189], v[6:9]
	v_mfma_f32_16x16x32_bf16 v[6:9], v[142:145], v[190:193], v[6:9]
	v_mfma_f32_16x16x32_bf16 v[2:5], v[154:157], v[186:189], v[2:5]
	v_mfma_f32_16x16x32_bf16 v[2:5], v[158:161], v[190:193], v[2:5]
	v_mfma_f32_16x16x32_bf16 v[18:21], v[154:157], v[178:181], v[18:21]
	v_mfma_f32_16x16x32_bf16 v[18:21], v[158:161], v[182:185], v[18:21]
	v_mfma_f32_16x16x32_bf16 v[34:37], v[154:157], v[170:173], v[34:37]
	v_mfma_f32_16x16x32_bf16 v[34:37], v[158:161], v[174:177], v[34:37]
	v_mfma_f32_16x16x32_bf16 v[50:53], v[154:157], v[162:165], v[50:53]
	v_mfma_f32_16x16x32_bf16 v[50:53], v[158:161], v[166:169], v[50:53]
	s_setprio 0
	s_barrier
	s_add_i32 s48, s48, 2
	s_add_u32 s46, s46, 0x100
	s_addc_u32 s47, s47, 0
	s_cmpk_gt_u32 s48, 0x55
	s_mov_b64 s[22:23], s[24:25]
	s_cbranch_scc0 .LBB0_1007
	s_and_b64 vcc, exec, s[18:19]
	s_cbranch_vccz .LBB0_1010
	s_barrier
